# uniform-depth counted waits: every phase retires the DMA pair issued five phases earlier (vmcnt(10) in all phases that need one; phases 4/8 no longer retire after four)
# speedup vs baseline: 1.0150x; 1.0031x over previous
.Lg131_noy:
	ds_read_b128 v[152:155], v149
	ds_read_b128 v[156:159], v149 offset:1024
	ds_read_b128 v[160:163], v149 offset:2048
	ds_read_b128 v[164:167], v149 offset:3072
	s_add_u32 s26, s20, 0xfffc0080
	s_addc_u32 s27, s21, -1
	s_cmp_eq_u32 s57, 12
	s_cselect_b32 s29, s13, s27
	s_cselect_b32 s28, s53, s26
	s_cselect_b32 s27, s11, s56
	s_cselect_b32 s26, s54, s55
	s_add_i32 m0, s19, 0xc000
	ds_read_b128 v[168:171], v150
	ds_read_b128 v[172:175], v150 offset:1024
	ds_read_b128 v[176:179], v150 offset:2048
	ds_read_b128 v[180:183], v150 offset:3072
	ds_read_b128 v[184:187], v150 offset:4096
	ds_read_b128 v[188:191], v150 offset:5120
	ds_read_b128 v[192:195], v150 offset:6144
	ds_read_b128 v[196:199], v150 offset:7168
	global_load_lds_dwordx4 v136, s[20:21]
	s_add_i32 m0, s19, 0xe000
	s_nop 0
	global_load_lds_dwordx4 v138, s[20:21]
	s_waitcnt lgkmcnt(8)
	s_waitcnt vmcnt(10)
	s_barrier
	s_waitcnt lgkmcnt(0)
	s_waitcnt lgkmcnt(0)
	v_mfma_f32_16x16x32_bf16 v[124:127], v[152:155], v[168:171], 0
	v_mfma_f32_16x16x32_bf16 v[120:123], v[160:163], v[168:171], 0
	v_mfma_f32_16x16x32_bf16 v[108:111], v[152:155], v[176:179], 0
	v_mfma_f32_16x16x32_bf16 v[104:107], v[160:163], v[176:179], 0
	v_mfma_f32_16x16x32_bf16 v[92:95], v[152:155], v[184:187], 0
	v_mfma_f32_16x16x32_bf16 v[88:91], v[160:163], v[184:187], 0
	v_mfma_f32_16x16x32_bf16 v[76:79], v[152:155], v[192:195], 0
	v_mfma_f32_16x16x32_bf16 v[72:75], v[160:163], v[192:195], 0
	v_mfma_f32_16x16x32_bf16 v[124:127], v[156:159], v[172:175], v[124:127]
	v_mfma_f32_16x16x32_bf16 v[120:123], v[164:167], v[172:175], v[120:123]
	v_mfma_f32_16x16x32_bf16 v[108:111], v[156:159], v[180:183], v[108:111]
	v_mfma_f32_16x16x32_bf16 v[104:107], v[164:167], v[180:183], v[104:107]
	v_mfma_f32_16x16x32_bf16 v[92:95], v[156:159], v[188:191], v[92:95]
	v_mfma_f32_16x16x32_bf16 v[88:91], v[164:167], v[188:191], v[88:91]
	v_mfma_f32_16x16x32_bf16 v[76:79], v[156:159], v[196:199], v[76:79]
	v_mfma_f32_16x16x32_bf16 v[72:75], v[164:167], v[196:199], v[72:75]
	s_barrier
	s_add_i32 s58, s47, s38
	s_add_u32 s80, s26, 0x80
	s_addc_u32 s81, s27, 0
	s_mov_b32 m0, s58
	ds_read_b128 v[200:203], v151
	ds_read_b128 v[204:207], v151 offset:1024
	ds_read_b128 v[208:211], v151 offset:2048
	ds_read_b128 v[212:215], v151 offset:3072
	global_load_lds_dwordx4 v132, s[26:27]
	s_add_i32 m0, s58, 0x2000
	s_nop 0
	global_load_lds_dwordx4 v128, s[26:27]
	s_waitcnt vmcnt(10)
	s_barrier
	s_waitcnt lgkmcnt(0)
	s_waitcnt lgkmcnt(0)
	v_mfma_f32_16x16x32_bf16 v[116:119], v[200:203], v[168:171], 0
	v_mfma_f32_16x16x32_bf16 v[112:115], v[208:211], v[168:171], 0
	v_mfma_f32_16x16x32_bf16 v[100:103], v[200:203], v[176:179], 0
	v_mfma_f32_16x16x32_bf16 v[96:99], v[208:211], v[176:179], 0
	v_mfma_f32_16x16x32_bf16 v[84:87], v[200:203], v[184:187], 0
	v_mfma_f32_16x16x32_bf16 v[80:83], v[208:211], v[184:187], 0
	v_mfma_f32_16x16x32_bf16 v[68:71], v[200:203], v[192:195], 0
	v_mfma_f32_16x16x32_bf16 v[64:67], v[208:211], v[192:195], 0
	v_mfma_f32_16x16x32_bf16 v[116:119], v[204:207], v[172:175], v[116:119]
	v_mfma_f32_16x16x32_bf16 v[112:115], v[212:215], v[172:175], v[112:115]
	v_mfma_f32_16x16x32_bf16 v[100:103], v[204:207], v[180:183], v[100:103]
	v_mfma_f32_16x16x32_bf16 v[96:99], v[212:215], v[180:183], v[96:99]
	v_mfma_f32_16x16x32_bf16 v[84:87], v[204:207], v[188:191], v[84:87]
	v_mfma_f32_16x16x32_bf16 v[80:83], v[212:215], v[188:191], v[80:83]
	v_mfma_f32_16x16x32_bf16 v[68:71], v[204:207], v[196:199], v[68:71]
	v_mfma_f32_16x16x32_bf16 v[64:67], v[212:215], v[196:199], v[64:67]
	s_mov_b32 m0, s19
	s_add_u32 s82, s28, 0x80
	s_addc_u32 s83, s29, 0
	s_barrier
	ds_read_b128 v[168:171], v150 offset:16384
	ds_read_b128 v[172:175], v150 offset:17408
	ds_read_b128 v[176:179], v150 offset:18432
	ds_read_b128 v[180:183], v150 offset:19456
	ds_read_b128 v[184:187], v150 offset:20480
	ds_read_b128 v[188:191], v150 offset:21504
	ds_read_b128 v[192:195], v150 offset:22528
	ds_read_b128 v[196:199], v150 offset:23552
	global_load_lds_dwordx4 v134, s[28:29]
	s_mov_b32 m0, s42
	s_nop 0
	global_load_lds_dwordx4 v130, s[28:29]
	s_barrier
	s_waitcnt lgkmcnt(0)
	s_waitcnt lgkmcnt(0)
	v_mfma_f32_16x16x32_bf16 v[60:63], v[152:155], v[168:171], 0
	v_mfma_f32_16x16x32_bf16 v[56:59], v[160:163], v[168:171], 0
	v_mfma_f32_16x16x32_bf16 v[44:47], v[152:155], v[176:179], 0
	v_mfma_f32_16x16x32_bf16 v[40:43], v[160:163], v[176:179], 0
	v_mfma_f32_16x16x32_bf16 v[28:31], v[152:155], v[184:187], 0
	v_mfma_f32_16x16x32_bf16 v[24:27], v[160:163], v[184:187], 0
	v_mfma_f32_16x16x32_bf16 v[12:15], v[152:155], v[192:195], 0
	v_mfma_f32_16x16x32_bf16 v[8:11], v[160:163], v[192:195], 0
	v_mfma_f32_16x16x32_bf16 v[60:63], v[156:159], v[172:175], v[60:63]
	v_mfma_f32_16x16x32_bf16 v[56:59], v[164:167], v[172:175], v[56:59]
	v_mfma_f32_16x16x32_bf16 v[44:47], v[156:159], v[180:183], v[44:47]
	v_mfma_f32_16x16x32_bf16 v[40:43], v[164:167], v[180:183], v[40:43]
	v_mfma_f32_16x16x32_bf16 v[28:31], v[156:159], v[188:191], v[28:31]
	v_mfma_f32_16x16x32_bf16 v[24:27], v[164:167], v[188:191], v[24:27]
	v_mfma_f32_16x16x32_bf16 v[12:15], v[156:159], v[196:199], v[12:15]
	v_mfma_f32_16x16x32_bf16 v[8:11], v[164:167], v[196:199], v[8:11]
	s_barrier
	s_add_u32 s58, s26, 0x40000
	s_addc_u32 s59, s27, 0
	s_add_i32 s60, s48, s38
	s_mov_b32 m0, s60
	s_nop 0
	global_load_lds_dwordx4 v132, s[58:59]
	s_add_i32 m0, s60, 0x2000
	s_nop 0
	global_load_lds_dwordx4 v128, s[58:59]
	s_waitcnt vmcnt(10)
	s_barrier
	v_mfma_f32_16x16x32_bf16 v[52:55], v[200:203], v[168:171], 0
	v_mfma_f32_16x16x32_bf16 v[48:51], v[208:211], v[168:171], 0
	v_mfma_f32_16x16x32_bf16 v[36:39], v[200:203], v[176:179], 0
	v_mfma_f32_16x16x32_bf16 v[32:35], v[208:211], v[176:179], 0
	v_mfma_f32_16x16x32_bf16 v[20:23], v[200:203], v[184:187], 0
	v_mfma_f32_16x16x32_bf16 v[16:19], v[208:211], v[184:187], 0
	v_mfma_f32_16x16x32_bf16 v[4:7], v[200:203], v[192:195], 0
	v_mfma_f32_16x16x32_bf16 v[0:3], v[208:211], v[192:195], 0
	v_mfma_f32_16x16x32_bf16 v[52:55], v[204:207], v[172:175], v[52:55]
	v_mfma_f32_16x16x32_bf16 v[48:51], v[212:215], v[172:175], v[48:51]
	v_mfma_f32_16x16x32_bf16 v[36:39], v[204:207], v[180:183], v[36:39]
	v_mfma_f32_16x16x32_bf16 v[32:35], v[212:215], v[180:183], v[32:35]
	v_mfma_f32_16x16x32_bf16 v[20:23], v[204:207], v[188:191], v[20:23]
	v_mfma_f32_16x16x32_bf16 v[16:19], v[212:215], v[188:191], v[16:19]
	v_mfma_f32_16x16x32_bf16 v[4:7], v[204:207], v[196:199], v[4:7]
	v_mfma_f32_16x16x32_bf16 v[0:3], v[212:215], v[196:199], v[0:3]
	s_add_i32 s58, 0, 0x18000
	v_add_u32_e32 v164, s58, v145
	s_barrier
	s_branch .Lg131_mid
.LBB0_131:
	ds_read_b128 v[152:155], v149
	ds_read_b128 v[156:159], v149 offset:1024
	ds_read_b128 v[160:163], v149 offset:2048
	ds_read_b128 v[164:167], v149 offset:3072
	s_add_u32 s26, s20, 0xfffc0080
	s_addc_u32 s27, s21, -1
	s_cmp_eq_u32 s57, 12
	s_cselect_b32 s29, s13, s27
	s_cselect_b32 s28, s53, s26
	s_cselect_b32 s27, s11, s56
	s_cselect_b32 s26, s54, s55
	s_add_i32 m0, s19, 0xc000
	ds_read_b128 v[168:171], v150
	ds_read_b128 v[172:175], v150 offset:1024
	ds_read_b128 v[176:179], v150 offset:2048
	ds_read_b128 v[180:183], v150 offset:3072
	ds_read_b128 v[184:187], v150 offset:4096
	ds_read_b128 v[188:191], v150 offset:5120
	ds_read_b128 v[192:195], v150 offset:6144
	ds_read_b128 v[196:199], v150 offset:7168
	global_load_lds_dwordx4 v136, s[20:21]
	s_add_i32 m0, s19, 0xe000
	s_nop 0
	global_load_lds_dwordx4 v138, s[20:21]
	s_waitcnt lgkmcnt(8)
	s_waitcnt vmcnt(10)
	s_barrier
	s_waitcnt lgkmcnt(0)
	s_waitcnt lgkmcnt(0)
	v_mfma_f32_16x16x32_bf16 v[124:127], v[152:155], v[168:171], v[124:127]
	v_mfma_f32_16x16x32_bf16 v[120:123], v[160:163], v[168:171], v[120:123]
	v_mfma_f32_16x16x32_bf16 v[108:111], v[152:155], v[176:179], v[108:111]
	v_mfma_f32_16x16x32_bf16 v[104:107], v[160:163], v[176:179], v[104:107]
	v_mfma_f32_16x16x32_bf16 v[92:95], v[152:155], v[184:187], v[92:95]
	v_mfma_f32_16x16x32_bf16 v[88:91], v[160:163], v[184:187], v[88:91]
	v_mfma_f32_16x16x32_bf16 v[76:79], v[152:155], v[192:195], v[76:79]
	v_mfma_f32_16x16x32_bf16 v[72:75], v[160:163], v[192:195], v[72:75]
	v_mfma_f32_16x16x32_bf16 v[124:127], v[156:159], v[172:175], v[124:127]
	v_mfma_f32_16x16x32_bf16 v[120:123], v[164:167], v[172:175], v[120:123]
	v_mfma_f32_16x16x32_bf16 v[108:111], v[156:159], v[180:183], v[108:111]
	v_mfma_f32_16x16x32_bf16 v[104:107], v[164:167], v[180:183], v[104:107]
	v_mfma_f32_16x16x32_bf16 v[92:95], v[156:159], v[188:191], v[92:95]
	v_mfma_f32_16x16x32_bf16 v[88:91], v[164:167], v[188:191], v[88:91]
	v_mfma_f32_16x16x32_bf16 v[76:79], v[156:159], v[196:199], v[76:79]
	v_mfma_f32_16x16x32_bf16 v[72:75], v[164:167], v[196:199], v[72:75]
	s_barrier
	s_add_i32 s58, s47, s38
	s_add_u32 s80, s26, 0x80
	s_addc_u32 s81, s27, 0
	s_mov_b32 m0, s58
	ds_read_b128 v[200:203], v151
	ds_read_b128 v[204:207], v151 offset:1024
	ds_read_b128 v[208:211], v151 offset:2048
	ds_read_b128 v[212:215], v151 offset:3072
	global_load_lds_dwordx4 v132, s[26:27]
	s_add_i32 m0, s58, 0x2000
	s_nop 0
	global_load_lds_dwordx4 v128, s[26:27]
	s_waitcnt vmcnt(10)
	s_barrier
	s_waitcnt lgkmcnt(0)
	s_waitcnt lgkmcnt(0)
	v_mfma_f32_16x16x32_bf16 v[116:119], v[200:203], v[168:171], v[116:119]
	v_mfma_f32_16x16x32_bf16 v[112:115], v[208:211], v[168:171], v[112:115]
	v_mfma_f32_16x16x32_bf16 v[100:103], v[200:203], v[176:179], v[100:103]
	v_mfma_f32_16x16x32_bf16 v[96:99], v[208:211], v[176:179], v[96:99]
	v_mfma_f32_16x16x32_bf16 v[84:87], v[200:203], v[184:187], v[84:87]
	v_mfma_f32_16x16x32_bf16 v[80:83], v[208:211], v[184:187], v[80:83]
	v_mfma_f32_16x16x32_bf16 v[68:71], v[200:203], v[192:195], v[68:71]
	v_mfma_f32_16x16x32_bf16 v[64:67], v[208:211], v[192:195], v[64:67]
	v_mfma_f32_16x16x32_bf16 v[116:119], v[204:207], v[172:175], v[116:119]
	v_mfma_f32_16x16x32_bf16 v[112:115], v[212:215], v[172:175], v[112:115]
	v_mfma_f32_16x16x32_bf16 v[100:103], v[204:207], v[180:183], v[100:103]
	v_mfma_f32_16x16x32_bf16 v[96:99], v[212:215], v[180:183], v[96:99]
	v_mfma_f32_16x16x32_bf16 v[84:87], v[204:207], v[188:191], v[84:87]
	v_mfma_f32_16x16x32_bf16 v[80:83], v[212:215], v[188:191], v[80:83]
	v_mfma_f32_16x16x32_bf16 v[68:71], v[204:207], v[196:199], v[68:71]
	v_mfma_f32_16x16x32_bf16 v[64:67], v[212:215], v[196:199], v[64:67]
	s_mov_b32 m0, s19
	s_add_u32 s82, s28, 0x80
	s_addc_u32 s83, s29, 0
	s_barrier
	ds_read_b128 v[168:171], v150 offset:16384
	ds_read_b128 v[172:175], v150 offset:17408
	ds_read_b128 v[176:179], v150 offset:18432
	ds_read_b128 v[180:183], v150 offset:19456
	ds_read_b128 v[184:187], v150 offset:20480
	ds_read_b128 v[188:191], v150 offset:21504
	ds_read_b128 v[192:195], v150 offset:22528
	ds_read_b128 v[196:199], v150 offset:23552
	global_load_lds_dwordx4 v134, s[28:29]
	s_mov_b32 m0, s42
	s_nop 0
	global_load_lds_dwordx4 v130, s[28:29]
	s_barrier
	s_waitcnt lgkmcnt(0)
	s_waitcnt lgkmcnt(0)
	v_mfma_f32_16x16x32_bf16 v[60:63], v[152:155], v[168:171], v[60:63]
	v_mfma_f32_16x16x32_bf16 v[56:59], v[160:163], v[168:171], v[56:59]
	v_mfma_f32_16x16x32_bf16 v[44:47], v[152:155], v[176:179], v[44:47]
	v_mfma_f32_16x16x32_bf16 v[40:43], v[160:163], v[176:179], v[40:43]
	v_mfma_f32_16x16x32_bf16 v[28:31], v[152:155], v[184:187], v[28:31]
	v_mfma_f32_16x16x32_bf16 v[24:27], v[160:163], v[184:187], v[24:27]
	v_mfma_f32_16x16x32_bf16 v[12:15], v[152:155], v[192:195], v[12:15]
	v_mfma_f32_16x16x32_bf16 v[8:11], v[160:163], v[192:195], v[8:11]
	v_mfma_f32_16x16x32_bf16 v[60:63], v[156:159], v[172:175], v[60:63]
	v_mfma_f32_16x16x32_bf16 v[56:59], v[164:167], v[172:175], v[56:59]
	v_mfma_f32_16x16x32_bf16 v[44:47], v[156:159], v[180:183], v[44:47]
	v_mfma_f32_16x16x32_bf16 v[40:43], v[164:167], v[180:183], v[40:43]
	v_mfma_f32_16x16x32_bf16 v[28:31], v[156:159], v[188:191], v[28:31]
	v_mfma_f32_16x16x32_bf16 v[24:27], v[164:167], v[188:191], v[24:27]
	v_mfma_f32_16x16x32_bf16 v[12:15], v[156:159], v[196:199], v[12:15]
	v_mfma_f32_16x16x32_bf16 v[8:11], v[164:167], v[196:199], v[8:11]
	s_barrier
	s_add_u32 s58, s26, 0x40000
	s_addc_u32 s59, s27, 0
	s_add_i32 s60, s48, s38
	s_mov_b32 m0, s60
	s_nop 0
	global_load_lds_dwordx4 v132, s[58:59]
	s_add_i32 m0, s60, 0x2000
	s_nop 0
	global_load_lds_dwordx4 v128, s[58:59]
	s_waitcnt vmcnt(10)
	s_barrier
	v_mfma_f32_16x16x32_bf16 v[52:55], v[200:203], v[168:171], v[52:55]
	v_mfma_f32_16x16x32_bf16 v[48:51], v[208:211], v[168:171], v[48:51]
	v_mfma_f32_16x16x32_bf16 v[36:39], v[200:203], v[176:179], v[36:39]
	v_mfma_f32_16x16x32_bf16 v[32:35], v[208:211], v[176:179], v[32:35]
	v_mfma_f32_16x16x32_bf16 v[20:23], v[200:203], v[184:187], v[20:23]
	v_mfma_f32_16x16x32_bf16 v[16:19], v[208:211], v[184:187], v[16:19]
	v_mfma_f32_16x16x32_bf16 v[4:7], v[200:203], v[192:195], v[4:7]
	v_mfma_f32_16x16x32_bf16 v[0:3], v[208:211], v[192:195], v[0:3]
	v_mfma_f32_16x16x32_bf16 v[52:55], v[204:207], v[172:175], v[52:55]
	v_mfma_f32_16x16x32_bf16 v[48:51], v[212:215], v[172:175], v[48:51]
	v_mfma_f32_16x16x32_bf16 v[36:39], v[204:207], v[180:183], v[36:39]
	v_mfma_f32_16x16x32_bf16 v[32:35], v[212:215], v[180:183], v[32:35]
	v_mfma_f32_16x16x32_bf16 v[20:23], v[204:207], v[188:191], v[20:23]
	v_mfma_f32_16x16x32_bf16 v[16:19], v[212:215], v[188:191], v[16:19]
	v_mfma_f32_16x16x32_bf16 v[4:7], v[204:207], v[196:199], v[4:7]
	v_mfma_f32_16x16x32_bf16 v[0:3], v[212:215], v[196:199], v[0:3]
	s_add_i32 s58, 0, 0x18000
	v_add_u32_e32 v164, s58, v145
	s_barrier
.Lg131_mid:
	ds_read_b128 v[152:155], v164
	ds_read_b128 v[156:159], v164 offset:1024
	ds_read_b128 v[160:163], v164 offset:2048
	ds_read_b128 v[164:167], v164 offset:3072
	s_add_u32 s28, s28, 0x40000
	s_addc_u32 s29, s29, 0
	s_mov_b32 m0, s43
	ds_read_b128 v[168:171], v150 offset:32768
	ds_read_b128 v[172:175], v150 offset:33792
	ds_read_b128 v[176:179], v150 offset:34816
	ds_read_b128 v[180:183], v150 offset:35840
	ds_read_b128 v[184:187], v150 offset:36864
	ds_read_b128 v[188:191], v150 offset:37888
	ds_read_b128 v[192:195], v150 offset:38912
	ds_read_b128 v[196:199], v150 offset:39936
	global_load_lds_dwordx4 v134, s[28:29]
	s_mov_b32 m0, s44
	s_nop 0
	global_load_lds_dwordx4 v130, s[28:29]
	s_waitcnt lgkmcnt(8)
	s_waitcnt vmcnt(10)
	s_barrier
	s_waitcnt lgkmcnt(0)
	s_waitcnt lgkmcnt(0)
	v_mfma_f32_16x16x32_bf16 v[124:127], v[152:155], v[168:171], v[124:127]
	v_mfma_f32_16x16x32_bf16 v[120:123], v[160:163], v[168:171], v[120:123]
	v_mfma_f32_16x16x32_bf16 v[108:111], v[152:155], v[176:179], v[108:111]
	v_mfma_f32_16x16x32_bf16 v[104:107], v[160:163], v[176:179], v[104:107]
	v_mfma_f32_16x16x32_bf16 v[92:95], v[152:155], v[184:187], v[92:95]
	v_mfma_f32_16x16x32_bf16 v[88:91], v[160:163], v[184:187], v[88:91]
	v_mfma_f32_16x16x32_bf16 v[76:79], v[152:155], v[192:195], v[76:79]
	v_mfma_f32_16x16x32_bf16 v[72:75], v[160:163], v[192:195], v[72:75]
	v_mfma_f32_16x16x32_bf16 v[124:127], v[156:159], v[172:175], v[124:127]
	v_mfma_f32_16x16x32_bf16 v[120:123], v[164:167], v[172:175], v[120:123]
	v_mfma_f32_16x16x32_bf16 v[108:111], v[156:159], v[180:183], v[108:111]
	v_mfma_f32_16x16x32_bf16 v[104:107], v[164:167], v[180:183], v[104:107]
	v_mfma_f32_16x16x32_bf16 v[92:95], v[156:159], v[188:191], v[92:95]
	v_mfma_f32_16x16x32_bf16 v[88:91], v[164:167], v[188:191], v[88:91]
	v_mfma_f32_16x16x32_bf16 v[76:79], v[156:159], v[196:199], v[76:79]
	v_mfma_f32_16x16x32_bf16 v[72:75], v[164:167], v[196:199], v[72:75]
	s_barrier
	s_add_i32 s28, 0, 0x1c000
	s_add_i32 s29, s58, s38
	v_add_u32_e32 v212, s28, v145
	s_mov_b32 m0, s29
	ds_read_b128 v[200:203], v212
	ds_read_b128 v[204:207], v212 offset:1024
	ds_read_b128 v[208:211], v212 offset:2048
	ds_read_b128 v[212:215], v212 offset:3072
	global_load_lds_dwordx4 v132, s[80:81]
	s_add_i32 m0, s29, 0x2000
	s_nop 0
	global_load_lds_dwordx4 v128, s[80:81]
	s_waitcnt vmcnt(10)
	s_barrier
	s_waitcnt lgkmcnt(0)
	s_waitcnt lgkmcnt(0)
	v_mfma_f32_16x16x32_bf16 v[116:119], v[200:203], v[168:171], v[116:119]
	v_mfma_f32_16x16x32_bf16 v[112:115], v[208:211], v[168:171], v[112:115]
	v_mfma_f32_16x16x32_bf16 v[100:103], v[200:203], v[176:179], v[100:103]
	v_mfma_f32_16x16x32_bf16 v[96:99], v[208:211], v[176:179], v[96:99]
	v_mfma_f32_16x16x32_bf16 v[84:87], v[200:203], v[184:187], v[84:87]
	v_mfma_f32_16x16x32_bf16 v[80:83], v[208:211], v[184:187], v[80:83]
	v_mfma_f32_16x16x32_bf16 v[68:71], v[200:203], v[192:195], v[68:71]
	v_mfma_f32_16x16x32_bf16 v[64:67], v[208:211], v[192:195], v[64:67]
	v_mfma_f32_16x16x32_bf16 v[116:119], v[204:207], v[172:175], v[116:119]
	v_mfma_f32_16x16x32_bf16 v[112:115], v[212:215], v[172:175], v[112:115]
	v_mfma_f32_16x16x32_bf16 v[100:103], v[204:207], v[180:183], v[100:103]
	v_mfma_f32_16x16x32_bf16 v[96:99], v[212:215], v[180:183], v[96:99]
	v_mfma_f32_16x16x32_bf16 v[84:87], v[204:207], v[188:191], v[84:87]
	v_mfma_f32_16x16x32_bf16 v[80:83], v[212:215], v[188:191], v[80:83]
	v_mfma_f32_16x16x32_bf16 v[68:71], v[204:207], v[196:199], v[68:71]
	v_mfma_f32_16x16x32_bf16 v[64:67], v[212:215], v[196:199], v[64:67]
	s_mov_b32 m0, s45
	s_barrier
	ds_read_b128 v[168:171], v150 offset:49152
	ds_read_b128 v[172:175], v150 offset:50176
	ds_read_b128 v[176:179], v150 offset:51200
	ds_read_b128 v[180:183], v150 offset:52224
	ds_read_b128 v[184:187], v150 offset:53248
	ds_read_b128 v[188:191], v150 offset:54272
	ds_read_b128 v[192:195], v150 offset:55296
	ds_read_b128 v[196:199], v150 offset:56320
	global_load_lds_dwordx4 v134, s[82:83]
	s_mov_b32 m0, s46
	s_nop 0
	global_load_lds_dwordx4 v130, s[82:83]
	s_barrier
	s_waitcnt lgkmcnt(0)
	s_waitcnt lgkmcnt(0)
	v_mfma_f32_16x16x32_bf16 v[60:63], v[152:155], v[168:171], v[60:63]
	v_mfma_f32_16x16x32_bf16 v[56:59], v[160:163], v[168:171], v[56:59]
	v_mfma_f32_16x16x32_bf16 v[44:47], v[152:155], v[176:179], v[44:47]
	v_mfma_f32_16x16x32_bf16 v[40:43], v[160:163], v[176:179], v[40:43]
	v_mfma_f32_16x16x32_bf16 v[28:31], v[152:155], v[184:187], v[28:31]
	v_mfma_f32_16x16x32_bf16 v[24:27], v[160:163], v[184:187], v[24:27]
	v_mfma_f32_16x16x32_bf16 v[12:15], v[152:155], v[192:195], v[12:15]
	v_mfma_f32_16x16x32_bf16 v[8:11], v[160:163], v[192:195], v[8:11]
	v_mfma_f32_16x16x32_bf16 v[60:63], v[156:159], v[172:175], v[60:63]
	v_mfma_f32_16x16x32_bf16 v[56:59], v[164:167], v[172:175], v[56:59]
	v_mfma_f32_16x16x32_bf16 v[44:47], v[156:159], v[180:183], v[44:47]
	v_mfma_f32_16x16x32_bf16 v[40:43], v[164:167], v[180:183], v[40:43]
	v_mfma_f32_16x16x32_bf16 v[28:31], v[156:159], v[188:191], v[28:31]
	v_mfma_f32_16x16x32_bf16 v[24:27], v[164:167], v[188:191], v[24:27]
	v_mfma_f32_16x16x32_bf16 v[12:15], v[156:159], v[196:199], v[12:15]
	v_mfma_f32_16x16x32_bf16 v[8:11], v[164:167], v[196:199], v[8:11]
	s_barrier
	s_add_u32 s26, s26, 0x40080
	s_addc_u32 s27, s27, 0
	s_add_i32 s28, s28, s38
	s_mov_b32 m0, s28
	s_nop 0
	global_load_lds_dwordx4 v132, s[26:27]
	s_add_i32 m0, s28, 0x2000
	s_nop 0
	global_load_lds_dwordx4 v128, s[26:27]
	s_waitcnt vmcnt(10)
	s_barrier
	v_mfma_f32_16x16x32_bf16 v[52:55], v[200:203], v[168:171], v[52:55]
	v_mfma_f32_16x16x32_bf16 v[48:51], v[208:211], v[168:171], v[48:51]
	v_mfma_f32_16x16x32_bf16 v[36:39], v[200:203], v[176:179], v[36:39]
	v_mfma_f32_16x16x32_bf16 v[32:35], v[208:211], v[176:179], v[32:35]
	v_mfma_f32_16x16x32_bf16 v[20:23], v[200:203], v[184:187], v[20:23]
	v_mfma_f32_16x16x32_bf16 v[16:19], v[208:211], v[184:187], v[16:19]
	v_mfma_f32_16x16x32_bf16 v[4:7], v[200:203], v[192:195], v[4:7]
	v_mfma_f32_16x16x32_bf16 v[0:3], v[208:211], v[192:195], v[0:3]
	v_mfma_f32_16x16x32_bf16 v[52:55], v[204:207], v[172:175], v[52:55]
	v_mfma_f32_16x16x32_bf16 v[48:51], v[212:215], v[172:175], v[48:51]
	v_mfma_f32_16x16x32_bf16 v[36:39], v[204:207], v[180:183], v[36:39]
	v_mfma_f32_16x16x32_bf16 v[32:35], v[212:215], v[180:183], v[32:35]
	v_mfma_f32_16x16x32_bf16 v[20:23], v[204:207], v[188:191], v[20:23]
	v_mfma_f32_16x16x32_bf16 v[16:19], v[212:215], v[188:191], v[16:19]
	v_mfma_f32_16x16x32_bf16 v[4:7], v[204:207], v[196:199], v[4:7]
	v_mfma_f32_16x16x32_bf16 v[0:3], v[212:215], v[196:199], v[0:3]
	s_add_i32 s57, s57, 2
	s_add_u32 s20, s20, 0x100
	s_addc_u32 s21, s21, 0
	s_add_u32 s55, s55, 0x100
	s_addc_u32 s56, s56, 0
	s_cmp_gt_u32 s57, 13
	s_barrier
	s_cbranch_scc0 .LBB0_131
	s_setprio 0
	s_cmpk_gt_u32 s37, 0xff
	s_cbranch_scc1 .Lg131_nox
	s_barrier
	s_setprio 1

.Lg248_noy:
	ds_read_b128 v[144:147], v151
	ds_read_b128 v[156:159], v151 offset:1024
	ds_read_b128 v[160:163], v151 offset:2048
	ds_read_b128 v[164:167], v151 offset:3072
	s_add_u32 s26, s20, 0x100
	s_addc_u32 s27, s21, 0
	s_cmp_eq_u32 s59, 40
	s_cselect_b32 s31, s9, s27
	s_cselect_b32 s30, s8, s26
	s_cselect_b32 s29, s11, s58
	s_cselect_b32 s28, s10, s57
	s_add_i32 m0, s41, 0xc000
	ds_read_b128 v[168:171], v152
	ds_read_b128 v[172:175], v152 offset:1024
	ds_read_b128 v[176:179], v152 offset:2048
	ds_read_b128 v[180:183], v152 offset:3072
	ds_read_b128 v[184:187], v152 offset:4096
	ds_read_b128 v[188:191], v152 offset:5120
	ds_read_b128 v[192:195], v152 offset:6144
	ds_read_b128 v[196:199], v152 offset:7168
	global_load_lds_dwordx4 v136, s[20:21]
	s_add_i32 m0, s41, 0xe000
	s_nop 0
	global_load_lds_dwordx4 v138, s[20:21]
	s_waitcnt lgkmcnt(8)
	s_waitcnt vmcnt(10)
	s_barrier
	s_waitcnt lgkmcnt(0)
	s_waitcnt lgkmcnt(0)
	v_mfma_f32_16x16x32_bf16 v[124:127], v[144:147], v[168:171], 0
	v_mfma_f32_16x16x32_bf16 v[120:123], v[160:163], v[168:171], 0
	v_mfma_f32_16x16x32_bf16 v[108:111], v[144:147], v[176:179], 0
	v_mfma_f32_16x16x32_bf16 v[104:107], v[160:163], v[176:179], 0
	v_mfma_f32_16x16x32_bf16 v[92:95], v[144:147], v[184:187], 0
	v_mfma_f32_16x16x32_bf16 v[88:91], v[160:163], v[184:187], 0
	v_mfma_f32_16x16x32_bf16 v[76:79], v[144:147], v[192:195], 0
	v_mfma_f32_16x16x32_bf16 v[72:75], v[160:163], v[192:195], 0
	v_mfma_f32_16x16x32_bf16 v[124:127], v[156:159], v[172:175], v[124:127]
	v_mfma_f32_16x16x32_bf16 v[120:123], v[164:167], v[172:175], v[120:123]
	v_mfma_f32_16x16x32_bf16 v[108:111], v[156:159], v[180:183], v[108:111]
	v_mfma_f32_16x16x32_bf16 v[104:107], v[164:167], v[180:183], v[104:107]
	v_mfma_f32_16x16x32_bf16 v[92:95], v[156:159], v[188:191], v[92:95]
	v_mfma_f32_16x16x32_bf16 v[88:91], v[164:167], v[188:191], v[88:91]
	v_mfma_f32_16x16x32_bf16 v[76:79], v[156:159], v[196:199], v[76:79]
	v_mfma_f32_16x16x32_bf16 v[72:75], v[164:167], v[196:199], v[72:75]
	s_barrier
	s_add_i32 s20, s51, s40
	s_add_u32 s80, s28, 0x80
	s_addc_u32 s81, s29, 0
	s_mov_b32 m0, s20
	ds_read_b128 v[200:203], v153
	ds_read_b128 v[204:207], v153 offset:1024
	ds_read_b128 v[208:211], v153 offset:2048
	ds_read_b128 v[212:215], v153 offset:3072
	global_load_lds_dwordx4 v130, s[28:29]
	s_add_i32 m0, s20, 0x2000
	s_nop 0
	global_load_lds_dwordx4 v134, s[28:29]
	s_waitcnt vmcnt(10)
	s_barrier
	s_waitcnt lgkmcnt(0)
	s_waitcnt lgkmcnt(0)
	v_mfma_f32_16x16x32_bf16 v[116:119], v[200:203], v[168:171], 0
	v_mfma_f32_16x16x32_bf16 v[112:115], v[208:211], v[168:171], 0
	v_mfma_f32_16x16x32_bf16 v[100:103], v[200:203], v[176:179], 0
	v_mfma_f32_16x16x32_bf16 v[96:99], v[208:211], v[176:179], 0
	v_mfma_f32_16x16x32_bf16 v[84:87], v[200:203], v[184:187], 0
	v_mfma_f32_16x16x32_bf16 v[80:83], v[208:211], v[184:187], 0
	v_mfma_f32_16x16x32_bf16 v[68:71], v[200:203], v[192:195], 0
	v_mfma_f32_16x16x32_bf16 v[64:67], v[208:211], v[192:195], 0
	v_mfma_f32_16x16x32_bf16 v[116:119], v[204:207], v[172:175], v[116:119]
	v_mfma_f32_16x16x32_bf16 v[112:115], v[212:215], v[172:175], v[112:115]
	v_mfma_f32_16x16x32_bf16 v[100:103], v[204:207], v[180:183], v[100:103]
	v_mfma_f32_16x16x32_bf16 v[96:99], v[212:215], v[180:183], v[96:99]
	v_mfma_f32_16x16x32_bf16 v[84:87], v[204:207], v[188:191], v[84:87]
	v_mfma_f32_16x16x32_bf16 v[80:83], v[212:215], v[188:191], v[80:83]
	v_mfma_f32_16x16x32_bf16 v[68:71], v[204:207], v[196:199], v[68:71]
	v_mfma_f32_16x16x32_bf16 v[64:67], v[212:215], v[196:199], v[64:67]
	s_mov_b32 m0, s41
	s_add_u32 s82, s30, 0x80
	s_addc_u32 s83, s31, 0
	s_barrier
	ds_read_b128 v[168:171], v152 offset:16384
	ds_read_b128 v[172:175], v152 offset:17408
	ds_read_b128 v[176:179], v152 offset:18432
	ds_read_b128 v[180:183], v152 offset:19456
	ds_read_b128 v[184:187], v152 offset:20480
	ds_read_b128 v[188:191], v152 offset:21504
	ds_read_b128 v[192:195], v152 offset:22528
	ds_read_b128 v[196:199], v152 offset:23552
	global_load_lds_dwordx4 v128, s[30:31]
	s_mov_b32 m0, s42
	s_nop 0
	global_load_lds_dwordx4 v132, s[30:31]
	s_barrier
	s_waitcnt lgkmcnt(0)
	s_waitcnt lgkmcnt(0)
	v_mfma_f32_16x16x32_bf16 v[60:63], v[144:147], v[168:171], 0
	v_mfma_f32_16x16x32_bf16 v[56:59], v[160:163], v[168:171], 0
	v_mfma_f32_16x16x32_bf16 v[44:47], v[144:147], v[176:179], 0
	v_mfma_f32_16x16x32_bf16 v[40:43], v[160:163], v[176:179], 0
	v_mfma_f32_16x16x32_bf16 v[28:31], v[144:147], v[184:187], 0
	v_mfma_f32_16x16x32_bf16 v[24:27], v[160:163], v[184:187], 0
	v_mfma_f32_16x16x32_bf16 v[12:15], v[144:147], v[192:195], 0
	v_mfma_f32_16x16x32_bf16 v[8:11], v[160:163], v[192:195], 0
	v_mfma_f32_16x16x32_bf16 v[60:63], v[156:159], v[172:175], v[60:63]
	v_mfma_f32_16x16x32_bf16 v[56:59], v[164:167], v[172:175], v[56:59]
	v_mfma_f32_16x16x32_bf16 v[44:47], v[156:159], v[180:183], v[44:47]
	v_mfma_f32_16x16x32_bf16 v[40:43], v[164:167], v[180:183], v[40:43]
	v_mfma_f32_16x16x32_bf16 v[28:31], v[156:159], v[188:191], v[28:31]
	v_mfma_f32_16x16x32_bf16 v[24:27], v[164:167], v[188:191], v[24:27]
	v_mfma_f32_16x16x32_bf16 v[12:15], v[156:159], v[196:199], v[12:15]
	v_mfma_f32_16x16x32_bf16 v[8:11], v[164:167], v[196:199], v[8:11]
	s_barrier
	s_add_u32 s20, s28, 0xb0000
	s_addc_u32 s21, s29, 0
	s_add_i32 s60, s52, s40
	s_mov_b32 m0, s60
	s_nop 0
	global_load_lds_dwordx4 v130, s[20:21]
	s_add_i32 m0, s60, 0x2000
	s_nop 0
	global_load_lds_dwordx4 v134, s[20:21]
	s_waitcnt vmcnt(10)
	s_barrier
	v_mfma_f32_16x16x32_bf16 v[52:55], v[200:203], v[168:171], 0
	v_mfma_f32_16x16x32_bf16 v[48:51], v[208:211], v[168:171], 0
	v_mfma_f32_16x16x32_bf16 v[36:39], v[200:203], v[176:179], 0
	v_mfma_f32_16x16x32_bf16 v[32:35], v[208:211], v[176:179], 0
	v_mfma_f32_16x16x32_bf16 v[20:23], v[200:203], v[184:187], 0
	v_mfma_f32_16x16x32_bf16 v[16:19], v[208:211], v[184:187], 0
	v_mfma_f32_16x16x32_bf16 v[4:7], v[200:203], v[192:195], 0
	v_mfma_f32_16x16x32_bf16 v[0:3], v[208:211], v[192:195], 0
	v_mfma_f32_16x16x32_bf16 v[52:55], v[204:207], v[172:175], v[52:55]
	v_mfma_f32_16x16x32_bf16 v[48:51], v[212:215], v[172:175], v[48:51]
	v_mfma_f32_16x16x32_bf16 v[36:39], v[204:207], v[180:183], v[36:39]
	v_mfma_f32_16x16x32_bf16 v[32:35], v[212:215], v[180:183], v[32:35]
	v_mfma_f32_16x16x32_bf16 v[20:23], v[204:207], v[188:191], v[20:23]
	v_mfma_f32_16x16x32_bf16 v[16:19], v[212:215], v[188:191], v[16:19]
	v_mfma_f32_16x16x32_bf16 v[4:7], v[204:207], v[196:199], v[4:7]
	v_mfma_f32_16x16x32_bf16 v[0:3], v[212:215], v[196:199], v[0:3]
	s_add_i32 s60, 0, 0x18000
	v_add_u32_e32 v155, s60, v149
	s_barrier
	s_branch .Lg248_mid
.LBB0_248:
	ds_read_b128 v[144:147], v151
	ds_read_b128 v[156:159], v151 offset:1024
	ds_read_b128 v[160:163], v151 offset:2048
	ds_read_b128 v[164:167], v151 offset:3072
	s_add_u32 s26, s20, 0x100
	s_addc_u32 s27, s21, 0
	s_cmp_eq_u32 s59, 40
	s_cselect_b32 s31, s9, s27
	s_cselect_b32 s30, s8, s26
	s_cselect_b32 s29, s11, s58
	s_cselect_b32 s28, s10, s57
	s_add_i32 m0, s41, 0xc000
	ds_read_b128 v[168:171], v152
	ds_read_b128 v[172:175], v152 offset:1024
	ds_read_b128 v[176:179], v152 offset:2048
	ds_read_b128 v[180:183], v152 offset:3072
	ds_read_b128 v[184:187], v152 offset:4096
	ds_read_b128 v[188:191], v152 offset:5120
	ds_read_b128 v[192:195], v152 offset:6144
	ds_read_b128 v[196:199], v152 offset:7168
	global_load_lds_dwordx4 v136, s[20:21]
	s_add_i32 m0, s41, 0xe000
	s_nop 0
	global_load_lds_dwordx4 v138, s[20:21]
	s_waitcnt lgkmcnt(8)
	s_waitcnt vmcnt(10)
	s_barrier
	s_waitcnt lgkmcnt(0)
	s_waitcnt lgkmcnt(0)
	v_mfma_f32_16x16x32_bf16 v[124:127], v[144:147], v[168:171], v[124:127]
	v_mfma_f32_16x16x32_bf16 v[120:123], v[160:163], v[168:171], v[120:123]
	v_mfma_f32_16x16x32_bf16 v[108:111], v[144:147], v[176:179], v[108:111]
	v_mfma_f32_16x16x32_bf16 v[104:107], v[160:163], v[176:179], v[104:107]
	v_mfma_f32_16x16x32_bf16 v[92:95], v[144:147], v[184:187], v[92:95]
	v_mfma_f32_16x16x32_bf16 v[88:91], v[160:163], v[184:187], v[88:91]
	v_mfma_f32_16x16x32_bf16 v[76:79], v[144:147], v[192:195], v[76:79]
	v_mfma_f32_16x16x32_bf16 v[72:75], v[160:163], v[192:195], v[72:75]
	v_mfma_f32_16x16x32_bf16 v[124:127], v[156:159], v[172:175], v[124:127]
	v_mfma_f32_16x16x32_bf16 v[120:123], v[164:167], v[172:175], v[120:123]
	v_mfma_f32_16x16x32_bf16 v[108:111], v[156:159], v[180:183], v[108:111]
	v_mfma_f32_16x16x32_bf16 v[104:107], v[164:167], v[180:183], v[104:107]
	v_mfma_f32_16x16x32_bf16 v[92:95], v[156:159], v[188:191], v[92:95]
	v_mfma_f32_16x16x32_bf16 v[88:91], v[164:167], v[188:191], v[88:91]
	v_mfma_f32_16x16x32_bf16 v[76:79], v[156:159], v[196:199], v[76:79]
	v_mfma_f32_16x16x32_bf16 v[72:75], v[164:167], v[196:199], v[72:75]
	s_barrier
	s_add_i32 s20, s51, s40
	s_add_u32 s80, s28, 0x80
	s_addc_u32 s81, s29, 0
	s_mov_b32 m0, s20
	ds_read_b128 v[200:203], v153
	ds_read_b128 v[204:207], v153 offset:1024
	ds_read_b128 v[208:211], v153 offset:2048
	ds_read_b128 v[212:215], v153 offset:3072
	global_load_lds_dwordx4 v130, s[28:29]
	s_add_i32 m0, s20, 0x2000
	s_nop 0
	global_load_lds_dwordx4 v134, s[28:29]
	s_waitcnt vmcnt(10)
	s_barrier
	s_waitcnt lgkmcnt(0)
	s_waitcnt lgkmcnt(0)
	v_mfma_f32_16x16x32_bf16 v[116:119], v[200:203], v[168:171], v[116:119]
	v_mfma_f32_16x16x32_bf16 v[112:115], v[208:211], v[168:171], v[112:115]
	v_mfma_f32_16x16x32_bf16 v[100:103], v[200:203], v[176:179], v[100:103]
	v_mfma_f32_16x16x32_bf16 v[96:99], v[208:211], v[176:179], v[96:99]
	v_mfma_f32_16x16x32_bf16 v[84:87], v[200:203], v[184:187], v[84:87]
	v_mfma_f32_16x16x32_bf16 v[80:83], v[208:211], v[184:187], v[80:83]
	v_mfma_f32_16x16x32_bf16 v[68:71], v[200:203], v[192:195], v[68:71]
	v_mfma_f32_16x16x32_bf16 v[64:67], v[208:211], v[192:195], v[64:67]
	v_mfma_f32_16x16x32_bf16 v[116:119], v[204:207], v[172:175], v[116:119]
	v_mfma_f32_16x16x32_bf16 v[112:115], v[212:215], v[172:175], v[112:115]
	v_mfma_f32_16x16x32_bf16 v[100:103], v[204:207], v[180:183], v[100:103]
	v_mfma_f32_16x16x32_bf16 v[96:99], v[212:215], v[180:183], v[96:99]
	v_mfma_f32_16x16x32_bf16 v[84:87], v[204:207], v[188:191], v[84:87]
	v_mfma_f32_16x16x32_bf16 v[80:83], v[212:215], v[188:191], v[80:83]
	v_mfma_f32_16x16x32_bf16 v[68:71], v[204:207], v[196:199], v[68:71]
	v_mfma_f32_16x16x32_bf16 v[64:67], v[212:215], v[196:199], v[64:67]
	s_mov_b32 m0, s41
	s_add_u32 s82, s30, 0x80
	s_addc_u32 s83, s31, 0
	s_barrier
	ds_read_b128 v[168:171], v152 offset:16384
	ds_read_b128 v[172:175], v152 offset:17408
	ds_read_b128 v[176:179], v152 offset:18432
	ds_read_b128 v[180:183], v152 offset:19456
	ds_read_b128 v[184:187], v152 offset:20480
	ds_read_b128 v[188:191], v152 offset:21504
	ds_read_b128 v[192:195], v152 offset:22528
	ds_read_b128 v[196:199], v152 offset:23552
	global_load_lds_dwordx4 v128, s[30:31]
	s_mov_b32 m0, s42
	s_nop 0
	global_load_lds_dwordx4 v132, s[30:31]
	s_barrier
	s_waitcnt lgkmcnt(0)
	s_waitcnt lgkmcnt(0)
	v_mfma_f32_16x16x32_bf16 v[60:63], v[144:147], v[168:171], v[60:63]
	v_mfma_f32_16x16x32_bf16 v[56:59], v[160:163], v[168:171], v[56:59]
	v_mfma_f32_16x16x32_bf16 v[44:47], v[144:147], v[176:179], v[44:47]
	v_mfma_f32_16x16x32_bf16 v[40:43], v[160:163], v[176:179], v[40:43]
	v_mfma_f32_16x16x32_bf16 v[28:31], v[144:147], v[184:187], v[28:31]
	v_mfma_f32_16x16x32_bf16 v[24:27], v[160:163], v[184:187], v[24:27]
	v_mfma_f32_16x16x32_bf16 v[12:15], v[144:147], v[192:195], v[12:15]
	v_mfma_f32_16x16x32_bf16 v[8:11], v[160:163], v[192:195], v[8:11]
	v_mfma_f32_16x16x32_bf16 v[60:63], v[156:159], v[172:175], v[60:63]
	v_mfma_f32_16x16x32_bf16 v[56:59], v[164:167], v[172:175], v[56:59]
	v_mfma_f32_16x16x32_bf16 v[44:47], v[156:159], v[180:183], v[44:47]
	v_mfma_f32_16x16x32_bf16 v[40:43], v[164:167], v[180:183], v[40:43]
	v_mfma_f32_16x16x32_bf16 v[28:31], v[156:159], v[188:191], v[28:31]
	v_mfma_f32_16x16x32_bf16 v[24:27], v[164:167], v[188:191], v[24:27]
	v_mfma_f32_16x16x32_bf16 v[12:15], v[156:159], v[196:199], v[12:15]
	v_mfma_f32_16x16x32_bf16 v[8:11], v[164:167], v[196:199], v[8:11]
	s_barrier
	s_add_u32 s20, s28, 0xb0000
	s_addc_u32 s21, s29, 0
	s_add_i32 s60, s52, s40
	s_mov_b32 m0, s60
	s_nop 0
	global_load_lds_dwordx4 v130, s[20:21]
	s_add_i32 m0, s60, 0x2000
	s_nop 0
	global_load_lds_dwordx4 v134, s[20:21]
	s_waitcnt vmcnt(10)
	s_barrier
	v_mfma_f32_16x16x32_bf16 v[52:55], v[200:203], v[168:171], v[52:55]
	v_mfma_f32_16x16x32_bf16 v[48:51], v[208:211], v[168:171], v[48:51]
	v_mfma_f32_16x16x32_bf16 v[36:39], v[200:203], v[176:179], v[36:39]
	v_mfma_f32_16x16x32_bf16 v[32:35], v[208:211], v[176:179], v[32:35]
	v_mfma_f32_16x16x32_bf16 v[20:23], v[200:203], v[184:187], v[20:23]
	v_mfma_f32_16x16x32_bf16 v[16:19], v[208:211], v[184:187], v[16:19]
	v_mfma_f32_16x16x32_bf16 v[4:7], v[200:203], v[192:195], v[4:7]
	v_mfma_f32_16x16x32_bf16 v[0:3], v[208:211], v[192:195], v[0:3]
	v_mfma_f32_16x16x32_bf16 v[52:55], v[204:207], v[172:175], v[52:55]
	v_mfma_f32_16x16x32_bf16 v[48:51], v[212:215], v[172:175], v[48:51]
	v_mfma_f32_16x16x32_bf16 v[36:39], v[204:207], v[180:183], v[36:39]
	v_mfma_f32_16x16x32_bf16 v[32:35], v[212:215], v[180:183], v[32:35]
	v_mfma_f32_16x16x32_bf16 v[20:23], v[204:207], v[188:191], v[20:23]
	v_mfma_f32_16x16x32_bf16 v[16:19], v[212:215], v[188:191], v[16:19]
	v_mfma_f32_16x16x32_bf16 v[4:7], v[204:207], v[196:199], v[4:7]
	v_mfma_f32_16x16x32_bf16 v[0:3], v[212:215], v[196:199], v[0:3]
	s_add_i32 s60, 0, 0x18000
	v_add_u32_e32 v155, s60, v149
	s_barrier
.Lg248_mid:
	ds_read_b128 v[144:147], v155
	ds_read_b128 v[156:159], v155 offset:1024
	ds_read_b128 v[160:163], v155 offset:2048
	ds_read_b128 v[164:167], v155 offset:3072
	s_add_u32 s20, s30, 0xb0000
	s_addc_u32 s21, s31, 0
	s_mov_b32 m0, s43
	ds_read_b128 v[168:171], v152 offset:32768
	ds_read_b128 v[172:175], v152 offset:33792
	ds_read_b128 v[176:179], v152 offset:34816
	ds_read_b128 v[180:183], v152 offset:35840
	ds_read_b128 v[184:187], v152 offset:36864
	ds_read_b128 v[188:191], v152 offset:37888
	ds_read_b128 v[192:195], v152 offset:38912
	ds_read_b128 v[196:199], v152 offset:39936
	global_load_lds_dwordx4 v128, s[20:21]
	s_mov_b32 m0, s44
	s_nop 0
	global_load_lds_dwordx4 v132, s[20:21]
	s_waitcnt lgkmcnt(8)
	s_waitcnt vmcnt(10)
	s_barrier
	s_waitcnt lgkmcnt(0)
	s_waitcnt lgkmcnt(0)
	v_mfma_f32_16x16x32_bf16 v[124:127], v[144:147], v[168:171], v[124:127]
	v_mfma_f32_16x16x32_bf16 v[120:123], v[160:163], v[168:171], v[120:123]
	v_mfma_f32_16x16x32_bf16 v[108:111], v[144:147], v[176:179], v[108:111]
	v_mfma_f32_16x16x32_bf16 v[104:107], v[160:163], v[176:179], v[104:107]
	v_mfma_f32_16x16x32_bf16 v[92:95], v[144:147], v[184:187], v[92:95]
	v_mfma_f32_16x16x32_bf16 v[88:91], v[160:163], v[184:187], v[88:91]
	v_mfma_f32_16x16x32_bf16 v[76:79], v[144:147], v[192:195], v[76:79]
	v_mfma_f32_16x16x32_bf16 v[72:75], v[160:163], v[192:195], v[72:75]
	v_mfma_f32_16x16x32_bf16 v[124:127], v[156:159], v[172:175], v[124:127]
	v_mfma_f32_16x16x32_bf16 v[120:123], v[164:167], v[172:175], v[120:123]
	v_mfma_f32_16x16x32_bf16 v[108:111], v[156:159], v[180:183], v[108:111]
	v_mfma_f32_16x16x32_bf16 v[104:107], v[164:167], v[180:183], v[104:107]
	v_mfma_f32_16x16x32_bf16 v[92:95], v[156:159], v[188:191], v[92:95]
	v_mfma_f32_16x16x32_bf16 v[88:91], v[164:167], v[188:191], v[88:91]
	v_mfma_f32_16x16x32_bf16 v[76:79], v[156:159], v[196:199], v[76:79]
	v_mfma_f32_16x16x32_bf16 v[72:75], v[164:167], v[196:199], v[72:75]
	s_barrier
	s_add_i32 s30, 0, 0x1c000
	s_add_i32 s20, s60, s40
	v_add_u32_e32 v155, s30, v149
	s_mov_b32 m0, s20
	ds_read_b128 v[200:203], v155
	ds_read_b128 v[204:207], v155 offset:1024
	ds_read_b128 v[208:211], v155 offset:2048
	ds_read_b128 v[212:215], v155 offset:3072
	global_load_lds_dwordx4 v130, s[80:81]
	s_add_i32 m0, s20, 0x2000
	s_nop 0
	global_load_lds_dwordx4 v134, s[80:81]
	s_waitcnt vmcnt(10)
	s_barrier
	s_waitcnt lgkmcnt(0)
	s_waitcnt lgkmcnt(0)
	v_mfma_f32_16x16x32_bf16 v[116:119], v[200:203], v[168:171], v[116:119]
	v_mfma_f32_16x16x32_bf16 v[112:115], v[208:211], v[168:171], v[112:115]
	v_mfma_f32_16x16x32_bf16 v[100:103], v[200:203], v[176:179], v[100:103]
	v_mfma_f32_16x16x32_bf16 v[96:99], v[208:211], v[176:179], v[96:99]
	v_mfma_f32_16x16x32_bf16 v[84:87], v[200:203], v[184:187], v[84:87]
	v_mfma_f32_16x16x32_bf16 v[80:83], v[208:211], v[184:187], v[80:83]
	v_mfma_f32_16x16x32_bf16 v[68:71], v[200:203], v[192:195], v[68:71]
	v_mfma_f32_16x16x32_bf16 v[64:67], v[208:211], v[192:195], v[64:67]
	v_mfma_f32_16x16x32_bf16 v[116:119], v[204:207], v[172:175], v[116:119]
	v_mfma_f32_16x16x32_bf16 v[112:115], v[212:215], v[172:175], v[112:115]
	v_mfma_f32_16x16x32_bf16 v[100:103], v[204:207], v[180:183], v[100:103]
	v_mfma_f32_16x16x32_bf16 v[96:99], v[212:215], v[180:183], v[96:99]
	v_mfma_f32_16x16x32_bf16 v[84:87], v[204:207], v[188:191], v[84:87]
	v_mfma_f32_16x16x32_bf16 v[80:83], v[212:215], v[188:191], v[80:83]
	v_mfma_f32_16x16x32_bf16 v[68:71], v[204:207], v[196:199], v[68:71]
	v_mfma_f32_16x16x32_bf16 v[64:67], v[212:215], v[196:199], v[64:67]
	s_mov_b32 m0, s46
	s_barrier
	ds_read_b128 v[168:171], v152 offset:49152
	ds_read_b128 v[172:175], v152 offset:50176
	ds_read_b128 v[176:179], v152 offset:51200
	ds_read_b128 v[180:183], v152 offset:52224
	ds_read_b128 v[184:187], v152 offset:53248
	ds_read_b128 v[188:191], v152 offset:54272
	ds_read_b128 v[192:195], v152 offset:55296
	ds_read_b128 v[196:199], v152 offset:56320
	global_load_lds_dwordx4 v128, s[82:83]
	s_mov_b32 m0, s47
	s_nop 0
	global_load_lds_dwordx4 v132, s[82:83]
	s_barrier
	s_waitcnt lgkmcnt(0)
	s_waitcnt lgkmcnt(0)
	v_mfma_f32_16x16x32_bf16 v[60:63], v[144:147], v[168:171], v[60:63]
	v_mfma_f32_16x16x32_bf16 v[56:59], v[160:163], v[168:171], v[56:59]
	v_mfma_f32_16x16x32_bf16 v[44:47], v[144:147], v[176:179], v[44:47]
	v_mfma_f32_16x16x32_bf16 v[40:43], v[160:163], v[176:179], v[40:43]
	v_mfma_f32_16x16x32_bf16 v[28:31], v[144:147], v[184:187], v[28:31]
	v_mfma_f32_16x16x32_bf16 v[24:27], v[160:163], v[184:187], v[24:27]
	v_mfma_f32_16x16x32_bf16 v[12:15], v[144:147], v[192:195], v[12:15]
	v_mfma_f32_16x16x32_bf16 v[8:11], v[160:163], v[192:195], v[8:11]
	v_mfma_f32_16x16x32_bf16 v[60:63], v[156:159], v[172:175], v[60:63]
	v_mfma_f32_16x16x32_bf16 v[56:59], v[164:167], v[172:175], v[56:59]
	v_mfma_f32_16x16x32_bf16 v[44:47], v[156:159], v[180:183], v[44:47]
	v_mfma_f32_16x16x32_bf16 v[40:43], v[164:167], v[180:183], v[40:43]
	v_mfma_f32_16x16x32_bf16 v[28:31], v[156:159], v[188:191], v[28:31]
	v_mfma_f32_16x16x32_bf16 v[24:27], v[164:167], v[188:191], v[24:27]
	v_mfma_f32_16x16x32_bf16 v[12:15], v[156:159], v[196:199], v[12:15]
	v_mfma_f32_16x16x32_bf16 v[8:11], v[164:167], v[196:199], v[8:11]
	s_barrier
	s_add_u32 s20, s28, 0xb0080
	s_addc_u32 s21, s29, 0
	s_add_i32 s28, s30, s40
	s_mov_b32 m0, s28
	s_nop 0
	global_load_lds_dwordx4 v130, s[20:21]
	s_add_i32 m0, s28, 0x2000
	s_nop 0
	global_load_lds_dwordx4 v134, s[20:21]
	s_waitcnt vmcnt(10)
	s_barrier
	v_mfma_f32_16x16x32_bf16 v[52:55], v[200:203], v[168:171], v[52:55]
	v_mfma_f32_16x16x32_bf16 v[48:51], v[208:211], v[168:171], v[48:51]
	v_mfma_f32_16x16x32_bf16 v[36:39], v[200:203], v[176:179], v[36:39]
	v_mfma_f32_16x16x32_bf16 v[32:35], v[208:211], v[176:179], v[32:35]
	v_mfma_f32_16x16x32_bf16 v[20:23], v[200:203], v[184:187], v[20:23]
	v_mfma_f32_16x16x32_bf16 v[16:19], v[208:211], v[184:187], v[16:19]
	v_mfma_f32_16x16x32_bf16 v[4:7], v[200:203], v[192:195], v[4:7]
	v_mfma_f32_16x16x32_bf16 v[0:3], v[208:211], v[192:195], v[0:3]
	v_mfma_f32_16x16x32_bf16 v[52:55], v[204:207], v[172:175], v[52:55]
	v_mfma_f32_16x16x32_bf16 v[48:51], v[212:215], v[172:175], v[48:51]
	v_mfma_f32_16x16x32_bf16 v[36:39], v[204:207], v[180:183], v[36:39]
	v_mfma_f32_16x16x32_bf16 v[32:35], v[212:215], v[180:183], v[32:35]
	v_mfma_f32_16x16x32_bf16 v[20:23], v[204:207], v[188:191], v[20:23]
	v_mfma_f32_16x16x32_bf16 v[16:19], v[212:215], v[188:191], v[16:19]
	v_mfma_f32_16x16x32_bf16 v[4:7], v[204:207], v[196:199], v[4:7]
	v_mfma_f32_16x16x32_bf16 v[0:3], v[212:215], v[196:199], v[0:3]
	s_add_i32 s59, s59, 2
	s_add_u32 s57, s57, 0x100
	s_addc_u32 s58, s58, 0
	s_cmp_gt_u32 s59, 41
	s_mov_b64 s[20:21], s[26:27]
	s_barrier
	s_cbranch_scc0 .LBB0_248
	s_setprio 0
	v_lshl_add_u32 v146, s56, 8, v148
	v_ashrrev_i32_e32 v147, 31, v146
	v_lshl_or_b32 v144, s12, 8, v150
	v_lshlrev_b64 v[156:157], 11, v[146:147]
	v_ashrrev_i32_e32 v145, 31, v144
	v_lshl_add_u64 v[156:157], s[14:15], 0, v[156:157]
	v_lshl_add_u64 v[166:167], v[144:145], 1, v[156:157]
	global_load_dwordx4 v[158:161], v[166:167], off
	global_load_dwordx4 v[162:165], v[166:167], off offset:256
	s_mov_b64 s[84:85], 0x8000
	s_mov_b64 s[86:87], 0x28000
	v_lshl_add_u64 v[232:233], v[166:167], 0, s[84:85]
	global_load_dwordx4 v[176:179], v[232:233], off
	global_load_dwordx4 v[180:183], v[232:233], off offset:256
	v_lshl_add_u64 v[232:233], v[232:233], 0, s[84:85]
	global_load_dwordx4 v[184:187], v[232:233], off
	global_load_dwordx4 v[188:191], v[232:233], off offset:256
	v_lshl_add_u64 v[232:233], v[232:233], 0, s[84:85]
	global_load_dwordx4 v[192:195], v[232:233], off
	global_load_dwordx4 v[196:199], v[232:233], off offset:256
	v_lshl_add_u64 v[232:233], v[232:233], 0, s[86:87]
	global_load_dwordx4 v[200:203], v[232:233], off
	global_load_dwordx4 v[204:207], v[232:233], off offset:256
	v_lshl_add_u64 v[232:233], v[232:233], 0, s[84:85]
	global_load_dwordx4 v[208:211], v[232:233], off
	global_load_dwordx4 v[212:215], v[232:233], off offset:256
	v_lshl_add_u64 v[232:233], v[232:233], 0, s[84:85]
	global_load_dwordx4 v[216:219], v[232:233], off
	global_load_dwordx4 v[220:223], v[232:233], off offset:256
	v_lshl_add_u64 v[232:233], v[232:233], 0, s[84:85]
	global_load_dwordx4 v[224:227], v[232:233], off
	global_load_dwordx4 v[228:231], v[232:233], off offset:256
	s_cmpk_gt_u32 s35, 0xff
	s_cbranch_scc1 .Lg248_nox
	s_barrier
	s_setprio 1

.Lg359_noy:
	ds_read_b128 v[128:131], v181
	ds_read_b128 v[132:135], v181 offset:1024
	ds_read_b128 v[136:139], v181 offset:2048
	ds_read_b128 v[166:169], v181 offset:3072
	s_add_u32 s38, s8, 0xfffc0080
	s_addc_u32 s39, s9, -1
	s_cmp_eq_u32 s75, 12
	s_cselect_b32 s41, s21, s39
	s_cselect_b32 s40, s71, s38
	s_cselect_b32 s39, s19, s74
	s_cselect_b32 s38, s72, s73
	s_add_i32 m0, s37, 0xc000
	ds_read_b128 v[170:173], v182
	ds_read_b128 v[174:177], v182 offset:1024
	ds_read_b128 v[192:195], v182 offset:2048
	ds_read_b128 v[196:199], v182 offset:3072
	ds_read_b128 v[200:203], v182 offset:4096
	ds_read_b128 v[204:207], v182 offset:5120
	ds_read_b128 v[208:211], v182 offset:6144
	ds_read_b128 v[212:215], v182 offset:7168
	global_load_lds_dwordx4 v158, s[8:9]
	s_add_i32 m0, s37, 0xe000
	s_nop 0
	global_load_lds_dwordx4 v160, s[8:9]
	s_waitcnt lgkmcnt(8)
	s_waitcnt vmcnt(10)
	s_barrier
	s_waitcnt lgkmcnt(0)
	s_waitcnt lgkmcnt(0)
	v_mfma_f32_16x16x32_bf16 v[124:127], v[128:131], v[170:173], 0
	v_mfma_f32_16x16x32_bf16 v[116:119], v[136:139], v[170:173], 0
	v_mfma_f32_16x16x32_bf16 v[108:111], v[128:131], v[192:195], 0
	v_mfma_f32_16x16x32_bf16 v[100:103], v[136:139], v[192:195], 0
	v_mfma_f32_16x16x32_bf16 v[92:95], v[128:131], v[200:203], 0
	v_mfma_f32_16x16x32_bf16 v[84:87], v[136:139], v[200:203], 0
	v_mfma_f32_16x16x32_bf16 v[76:79], v[128:131], v[208:211], 0
	v_mfma_f32_16x16x32_bf16 v[68:71], v[136:139], v[208:211], 0
	v_mfma_f32_16x16x32_bf16 v[124:127], v[132:135], v[174:177], v[124:127]
	v_mfma_f32_16x16x32_bf16 v[116:119], v[166:169], v[174:177], v[116:119]
	v_mfma_f32_16x16x32_bf16 v[108:111], v[132:135], v[196:199], v[108:111]
	v_mfma_f32_16x16x32_bf16 v[100:103], v[166:169], v[196:199], v[100:103]
	v_mfma_f32_16x16x32_bf16 v[92:95], v[132:135], v[204:207], v[92:95]
	v_mfma_f32_16x16x32_bf16 v[84:87], v[166:169], v[204:207], v[84:87]
	v_mfma_f32_16x16x32_bf16 v[76:79], v[132:135], v[212:215], v[76:79]
	v_mfma_f32_16x16x32_bf16 v[68:71], v[166:169], v[212:215], v[68:71]
	s_barrier
	s_add_i32 s76, s63, s46
	s_add_u32 s80, s38, 0x80
	s_addc_u32 s81, s39, 0
	s_mov_b32 m0, s76
	ds_read_b128 v[216:219], v183
	ds_read_b128 v[220:223], v183 offset:1024
	ds_read_b128 v[224:227], v183 offset:2048
	ds_read_b128 v[228:231], v183 offset:3072
	global_load_lds_dwordx4 v144, s[38:39]
	s_add_i32 m0, s76, 0x2000
	s_nop 0
	global_load_lds_dwordx4 v148, s[38:39]
	s_waitcnt vmcnt(10)
	s_barrier
	s_waitcnt lgkmcnt(0)
	s_waitcnt lgkmcnt(0)
	v_mfma_f32_16x16x32_bf16 v[120:123], v[216:219], v[170:173], 0
	v_mfma_f32_16x16x32_bf16 v[112:115], v[224:227], v[170:173], 0
	v_mfma_f32_16x16x32_bf16 v[104:107], v[216:219], v[192:195], 0
	v_mfma_f32_16x16x32_bf16 v[96:99], v[224:227], v[192:195], 0
	v_mfma_f32_16x16x32_bf16 v[88:91], v[216:219], v[200:203], 0
	v_mfma_f32_16x16x32_bf16 v[80:83], v[224:227], v[200:203], 0
	v_mfma_f32_16x16x32_bf16 v[72:75], v[216:219], v[208:211], 0
	v_mfma_f32_16x16x32_bf16 v[64:67], v[224:227], v[208:211], 0
	v_mfma_f32_16x16x32_bf16 v[120:123], v[220:223], v[174:177], v[120:123]
	v_mfma_f32_16x16x32_bf16 v[112:115], v[228:231], v[174:177], v[112:115]
	v_mfma_f32_16x16x32_bf16 v[104:107], v[220:223], v[196:199], v[104:107]
	v_mfma_f32_16x16x32_bf16 v[96:99], v[228:231], v[196:199], v[96:99]
	v_mfma_f32_16x16x32_bf16 v[88:91], v[220:223], v[204:207], v[88:91]
	v_mfma_f32_16x16x32_bf16 v[80:83], v[228:231], v[204:207], v[80:83]
	v_mfma_f32_16x16x32_bf16 v[72:75], v[220:223], v[212:215], v[72:75]
	v_mfma_f32_16x16x32_bf16 v[64:67], v[228:231], v[212:215], v[64:67]
	s_mov_b32 m0, s37
	s_add_u32 s82, s40, 0x80
	s_addc_u32 s83, s41, 0
	s_barrier
	ds_read_b128 v[170:173], v182 offset:16384
	ds_read_b128 v[174:177], v182 offset:17408
	ds_read_b128 v[192:195], v182 offset:18432
	ds_read_b128 v[196:199], v182 offset:19456
	ds_read_b128 v[200:203], v182 offset:20480
	ds_read_b128 v[204:207], v182 offset:21504
	ds_read_b128 v[208:211], v182 offset:22528
	ds_read_b128 v[212:215], v182 offset:23552
	global_load_lds_dwordx4 v142, s[40:41]
	s_mov_b32 m0, s51
	s_nop 0
	global_load_lds_dwordx4 v146, s[40:41]
	s_barrier
	s_waitcnt lgkmcnt(0)
	s_waitcnt lgkmcnt(0)
	v_mfma_f32_16x16x32_bf16 v[60:63], v[128:131], v[170:173], 0
	v_mfma_f32_16x16x32_bf16 v[52:55], v[136:139], v[170:173], 0
	v_mfma_f32_16x16x32_bf16 v[44:47], v[128:131], v[192:195], 0
	v_mfma_f32_16x16x32_bf16 v[36:39], v[136:139], v[192:195], 0
	v_mfma_f32_16x16x32_bf16 v[28:31], v[128:131], v[200:203], 0
	v_mfma_f32_16x16x32_bf16 v[20:23], v[136:139], v[200:203], 0
	v_mfma_f32_16x16x32_bf16 v[12:15], v[128:131], v[208:211], 0
	v_mfma_f32_16x16x32_bf16 v[4:7], v[136:139], v[208:211], 0
	v_mfma_f32_16x16x32_bf16 v[60:63], v[132:135], v[174:177], v[60:63]
	v_mfma_f32_16x16x32_bf16 v[52:55], v[166:169], v[174:177], v[52:55]
	v_mfma_f32_16x16x32_bf16 v[44:47], v[132:135], v[196:199], v[44:47]
	v_mfma_f32_16x16x32_bf16 v[36:39], v[166:169], v[196:199], v[36:39]
	v_mfma_f32_16x16x32_bf16 v[28:31], v[132:135], v[204:207], v[28:31]
	v_mfma_f32_16x16x32_bf16 v[20:23], v[166:169], v[204:207], v[20:23]
	v_mfma_f32_16x16x32_bf16 v[12:15], v[132:135], v[212:215], v[12:15]
	v_mfma_f32_16x16x32_bf16 v[4:7], v[166:169], v[212:215], v[4:7]
	s_barrier
	s_add_u32 s76, s38, 0x40000
	s_addc_u32 s77, s39, 0
	s_add_i32 s78, s64, s46
	s_mov_b32 m0, s78
	s_nop 0
	global_load_lds_dwordx4 v144, s[76:77]
	s_add_i32 m0, s78, 0x2000
	s_nop 0
	global_load_lds_dwordx4 v148, s[76:77]
	s_waitcnt vmcnt(10)
	s_barrier
	v_mfma_f32_16x16x32_bf16 v[56:59], v[216:219], v[170:173], 0
	v_mfma_f32_16x16x32_bf16 v[48:51], v[224:227], v[170:173], 0
	v_mfma_f32_16x16x32_bf16 v[40:43], v[216:219], v[192:195], 0
	v_mfma_f32_16x16x32_bf16 v[32:35], v[224:227], v[192:195], 0
	v_mfma_f32_16x16x32_bf16 v[24:27], v[216:219], v[200:203], 0
	v_mfma_f32_16x16x32_bf16 v[16:19], v[224:227], v[200:203], 0
	v_mfma_f32_16x16x32_bf16 v[8:11], v[216:219], v[208:211], 0
	v_mfma_f32_16x16x32_bf16 v[0:3], v[224:227], v[208:211], 0
	v_mfma_f32_16x16x32_bf16 v[56:59], v[220:223], v[174:177], v[56:59]
	v_mfma_f32_16x16x32_bf16 v[48:51], v[228:231], v[174:177], v[48:51]
	v_mfma_f32_16x16x32_bf16 v[40:43], v[220:223], v[196:199], v[40:43]
	v_mfma_f32_16x16x32_bf16 v[32:35], v[228:231], v[196:199], v[32:35]
	v_mfma_f32_16x16x32_bf16 v[24:27], v[220:223], v[204:207], v[24:27]
	v_mfma_f32_16x16x32_bf16 v[16:19], v[228:231], v[204:207], v[16:19]
	v_mfma_f32_16x16x32_bf16 v[8:11], v[220:223], v[212:215], v[8:11]
	v_mfma_f32_16x16x32_bf16 v[0:3], v[228:231], v[212:215], v[0:3]
	s_add_i32 s76, 0, 0x18000
	v_add_u32_e32 v150, s76, v179
	s_barrier
	s_branch .Lg359_mid
.LBB0_359:
	ds_read_b128 v[128:131], v181
	ds_read_b128 v[132:135], v181 offset:1024
	ds_read_b128 v[136:139], v181 offset:2048
	ds_read_b128 v[166:169], v181 offset:3072
	s_add_u32 s38, s8, 0xfffc0080
	s_addc_u32 s39, s9, -1
	s_cmp_eq_u32 s75, 12
	s_cselect_b32 s41, s21, s39
	s_cselect_b32 s40, s71, s38
	s_cselect_b32 s39, s19, s74
	s_cselect_b32 s38, s72, s73
	s_add_i32 m0, s37, 0xc000
	ds_read_b128 v[170:173], v182
	ds_read_b128 v[174:177], v182 offset:1024
	ds_read_b128 v[192:195], v182 offset:2048
	ds_read_b128 v[196:199], v182 offset:3072
	ds_read_b128 v[200:203], v182 offset:4096
	ds_read_b128 v[204:207], v182 offset:5120
	ds_read_b128 v[208:211], v182 offset:6144
	ds_read_b128 v[212:215], v182 offset:7168
	global_load_lds_dwordx4 v158, s[8:9]
	s_add_i32 m0, s37, 0xe000
	s_nop 0
	global_load_lds_dwordx4 v160, s[8:9]
	s_waitcnt lgkmcnt(8)
	s_waitcnt vmcnt(10)
	s_barrier
	s_waitcnt lgkmcnt(0)
	s_waitcnt lgkmcnt(0)
	v_mfma_f32_16x16x32_bf16 v[124:127], v[128:131], v[170:173], v[124:127]
	v_mfma_f32_16x16x32_bf16 v[116:119], v[136:139], v[170:173], v[116:119]
	v_mfma_f32_16x16x32_bf16 v[108:111], v[128:131], v[192:195], v[108:111]
	v_mfma_f32_16x16x32_bf16 v[100:103], v[136:139], v[192:195], v[100:103]
	v_mfma_f32_16x16x32_bf16 v[92:95], v[128:131], v[200:203], v[92:95]
	v_mfma_f32_16x16x32_bf16 v[84:87], v[136:139], v[200:203], v[84:87]
	v_mfma_f32_16x16x32_bf16 v[76:79], v[128:131], v[208:211], v[76:79]
	v_mfma_f32_16x16x32_bf16 v[68:71], v[136:139], v[208:211], v[68:71]
	v_mfma_f32_16x16x32_bf16 v[124:127], v[132:135], v[174:177], v[124:127]
	v_mfma_f32_16x16x32_bf16 v[116:119], v[166:169], v[174:177], v[116:119]
	v_mfma_f32_16x16x32_bf16 v[108:111], v[132:135], v[196:199], v[108:111]
	v_mfma_f32_16x16x32_bf16 v[100:103], v[166:169], v[196:199], v[100:103]
	v_mfma_f32_16x16x32_bf16 v[92:95], v[132:135], v[204:207], v[92:95]
	v_mfma_f32_16x16x32_bf16 v[84:87], v[166:169], v[204:207], v[84:87]
	v_mfma_f32_16x16x32_bf16 v[76:79], v[132:135], v[212:215], v[76:79]
	v_mfma_f32_16x16x32_bf16 v[68:71], v[166:169], v[212:215], v[68:71]
	s_barrier
	s_add_i32 s76, s63, s46
	s_add_u32 s80, s38, 0x80
	s_addc_u32 s81, s39, 0
	s_mov_b32 m0, s76
	ds_read_b128 v[216:219], v183
	ds_read_b128 v[220:223], v183 offset:1024
	ds_read_b128 v[224:227], v183 offset:2048
	ds_read_b128 v[228:231], v183 offset:3072
	global_load_lds_dwordx4 v144, s[38:39]
	s_add_i32 m0, s76, 0x2000
	s_nop 0
	global_load_lds_dwordx4 v148, s[38:39]
	s_waitcnt vmcnt(10)
	s_barrier
	s_waitcnt lgkmcnt(0)
	s_waitcnt lgkmcnt(0)
	v_mfma_f32_16x16x32_bf16 v[120:123], v[216:219], v[170:173], v[120:123]
	v_mfma_f32_16x16x32_bf16 v[112:115], v[224:227], v[170:173], v[112:115]
	v_mfma_f32_16x16x32_bf16 v[104:107], v[216:219], v[192:195], v[104:107]
	v_mfma_f32_16x16x32_bf16 v[96:99], v[224:227], v[192:195], v[96:99]
	v_mfma_f32_16x16x32_bf16 v[88:91], v[216:219], v[200:203], v[88:91]
	v_mfma_f32_16x16x32_bf16 v[80:83], v[224:227], v[200:203], v[80:83]
	v_mfma_f32_16x16x32_bf16 v[72:75], v[216:219], v[208:211], v[72:75]
	v_mfma_f32_16x16x32_bf16 v[64:67], v[224:227], v[208:211], v[64:67]
	v_mfma_f32_16x16x32_bf16 v[120:123], v[220:223], v[174:177], v[120:123]
	v_mfma_f32_16x16x32_bf16 v[112:115], v[228:231], v[174:177], v[112:115]
	v_mfma_f32_16x16x32_bf16 v[104:107], v[220:223], v[196:199], v[104:107]
	v_mfma_f32_16x16x32_bf16 v[96:99], v[228:231], v[196:199], v[96:99]
	v_mfma_f32_16x16x32_bf16 v[88:91], v[220:223], v[204:207], v[88:91]
	v_mfma_f32_16x16x32_bf16 v[80:83], v[228:231], v[204:207], v[80:83]
	v_mfma_f32_16x16x32_bf16 v[72:75], v[220:223], v[212:215], v[72:75]
	v_mfma_f32_16x16x32_bf16 v[64:67], v[228:231], v[212:215], v[64:67]
	s_mov_b32 m0, s37
	s_add_u32 s82, s40, 0x80
	s_addc_u32 s83, s41, 0
	s_barrier
	ds_read_b128 v[170:173], v182 offset:16384
	ds_read_b128 v[174:177], v182 offset:17408
	ds_read_b128 v[192:195], v182 offset:18432
	ds_read_b128 v[196:199], v182 offset:19456
	ds_read_b128 v[200:203], v182 offset:20480
	ds_read_b128 v[204:207], v182 offset:21504
	ds_read_b128 v[208:211], v182 offset:22528
	ds_read_b128 v[212:215], v182 offset:23552
	global_load_lds_dwordx4 v142, s[40:41]
	s_mov_b32 m0, s51
	s_nop 0
	global_load_lds_dwordx4 v146, s[40:41]
	s_barrier
	s_waitcnt lgkmcnt(0)
	s_waitcnt lgkmcnt(0)
	v_mfma_f32_16x16x32_bf16 v[60:63], v[128:131], v[170:173], v[60:63]
	v_mfma_f32_16x16x32_bf16 v[52:55], v[136:139], v[170:173], v[52:55]
	v_mfma_f32_16x16x32_bf16 v[44:47], v[128:131], v[192:195], v[44:47]
	v_mfma_f32_16x16x32_bf16 v[36:39], v[136:139], v[192:195], v[36:39]
	v_mfma_f32_16x16x32_bf16 v[28:31], v[128:131], v[200:203], v[28:31]
	v_mfma_f32_16x16x32_bf16 v[20:23], v[136:139], v[200:203], v[20:23]
	v_mfma_f32_16x16x32_bf16 v[12:15], v[128:131], v[208:211], v[12:15]
	v_mfma_f32_16x16x32_bf16 v[4:7], v[136:139], v[208:211], v[4:7]
	v_mfma_f32_16x16x32_bf16 v[60:63], v[132:135], v[174:177], v[60:63]
	v_mfma_f32_16x16x32_bf16 v[52:55], v[166:169], v[174:177], v[52:55]
	v_mfma_f32_16x16x32_bf16 v[44:47], v[132:135], v[196:199], v[44:47]
	v_mfma_f32_16x16x32_bf16 v[36:39], v[166:169], v[196:199], v[36:39]
	v_mfma_f32_16x16x32_bf16 v[28:31], v[132:135], v[204:207], v[28:31]
	v_mfma_f32_16x16x32_bf16 v[20:23], v[166:169], v[204:207], v[20:23]
	v_mfma_f32_16x16x32_bf16 v[12:15], v[132:135], v[212:215], v[12:15]
	v_mfma_f32_16x16x32_bf16 v[4:7], v[166:169], v[212:215], v[4:7]
	s_barrier
	s_add_u32 s76, s38, 0x40000
	s_addc_u32 s77, s39, 0
	s_add_i32 s78, s64, s46
	s_mov_b32 m0, s78
	s_nop 0
	global_load_lds_dwordx4 v144, s[76:77]
	s_add_i32 m0, s78, 0x2000
	s_nop 0
	global_load_lds_dwordx4 v148, s[76:77]
	s_waitcnt vmcnt(10)
	s_barrier
	v_mfma_f32_16x16x32_bf16 v[56:59], v[216:219], v[170:173], v[56:59]
	v_mfma_f32_16x16x32_bf16 v[48:51], v[224:227], v[170:173], v[48:51]
	v_mfma_f32_16x16x32_bf16 v[40:43], v[216:219], v[192:195], v[40:43]
	v_mfma_f32_16x16x32_bf16 v[32:35], v[224:227], v[192:195], v[32:35]
	v_mfma_f32_16x16x32_bf16 v[24:27], v[216:219], v[200:203], v[24:27]
	v_mfma_f32_16x16x32_bf16 v[16:19], v[224:227], v[200:203], v[16:19]
	v_mfma_f32_16x16x32_bf16 v[8:11], v[216:219], v[208:211], v[8:11]
	v_mfma_f32_16x16x32_bf16 v[0:3], v[224:227], v[208:211], v[0:3]
	v_mfma_f32_16x16x32_bf16 v[56:59], v[220:223], v[174:177], v[56:59]
	v_mfma_f32_16x16x32_bf16 v[48:51], v[228:231], v[174:177], v[48:51]
	v_mfma_f32_16x16x32_bf16 v[40:43], v[220:223], v[196:199], v[40:43]
	v_mfma_f32_16x16x32_bf16 v[32:35], v[228:231], v[196:199], v[32:35]
	v_mfma_f32_16x16x32_bf16 v[24:27], v[220:223], v[204:207], v[24:27]
	v_mfma_f32_16x16x32_bf16 v[16:19], v[228:231], v[204:207], v[16:19]
	v_mfma_f32_16x16x32_bf16 v[8:11], v[220:223], v[212:215], v[8:11]
	v_mfma_f32_16x16x32_bf16 v[0:3], v[228:231], v[212:215], v[0:3]
	s_add_i32 s76, 0, 0x18000
	v_add_u32_e32 v150, s76, v179
	s_barrier
.Lg359_mid:
	ds_read_b128 v[128:131], v150
	ds_read_b128 v[132:135], v150 offset:1024
	ds_read_b128 v[136:139], v150 offset:2048
	ds_read_b128 v[166:169], v150 offset:3072
	s_add_u32 s40, s40, 0x40000
	s_addc_u32 s41, s41, 0
	s_mov_b32 m0, s52
	ds_read_b128 v[170:173], v182 offset:32768
	ds_read_b128 v[174:177], v182 offset:33792
	ds_read_b128 v[192:195], v182 offset:34816
	ds_read_b128 v[196:199], v182 offset:35840
	ds_read_b128 v[200:203], v182 offset:36864
	ds_read_b128 v[204:207], v182 offset:37888
	ds_read_b128 v[208:211], v182 offset:38912
	ds_read_b128 v[212:215], v182 offset:39936
	global_load_lds_dwordx4 v142, s[40:41]
	s_mov_b32 m0, s53
	s_nop 0
	global_load_lds_dwordx4 v146, s[40:41]
	s_waitcnt lgkmcnt(8)
	s_waitcnt vmcnt(10)
	s_barrier
	s_waitcnt lgkmcnt(0)
	s_waitcnt lgkmcnt(0)
	v_mfma_f32_16x16x32_bf16 v[124:127], v[128:131], v[170:173], v[124:127]
	v_mfma_f32_16x16x32_bf16 v[116:119], v[136:139], v[170:173], v[116:119]
	v_mfma_f32_16x16x32_bf16 v[108:111], v[128:131], v[192:195], v[108:111]
	v_mfma_f32_16x16x32_bf16 v[100:103], v[136:139], v[192:195], v[100:103]
	v_mfma_f32_16x16x32_bf16 v[92:95], v[128:131], v[200:203], v[92:95]
	v_mfma_f32_16x16x32_bf16 v[84:87], v[136:139], v[200:203], v[84:87]
	v_mfma_f32_16x16x32_bf16 v[76:79], v[128:131], v[208:211], v[76:79]
	v_mfma_f32_16x16x32_bf16 v[68:71], v[136:139], v[208:211], v[68:71]
	v_mfma_f32_16x16x32_bf16 v[124:127], v[132:135], v[174:177], v[124:127]
	v_mfma_f32_16x16x32_bf16 v[116:119], v[166:169], v[174:177], v[116:119]
	v_mfma_f32_16x16x32_bf16 v[108:111], v[132:135], v[196:199], v[108:111]
	v_mfma_f32_16x16x32_bf16 v[100:103], v[166:169], v[196:199], v[100:103]
	v_mfma_f32_16x16x32_bf16 v[92:95], v[132:135], v[204:207], v[92:95]
	v_mfma_f32_16x16x32_bf16 v[84:87], v[166:169], v[204:207], v[84:87]
	v_mfma_f32_16x16x32_bf16 v[76:79], v[132:135], v[212:215], v[76:79]
	v_mfma_f32_16x16x32_bf16 v[68:71], v[166:169], v[212:215], v[68:71]
	s_barrier
	s_add_i32 s40, 0, 0x1c000
	s_add_i32 s41, s76, s46
	v_add_u32_e32 v150, s40, v179
	s_mov_b32 m0, s41
	ds_read_b128 v[216:219], v150
	ds_read_b128 v[220:223], v150 offset:1024
	ds_read_b128 v[224:227], v150 offset:2048
	ds_read_b128 v[228:231], v150 offset:3072
	global_load_lds_dwordx4 v144, s[80:81]
	s_add_i32 m0, s41, 0x2000
	s_nop 0
	global_load_lds_dwordx4 v148, s[80:81]
	s_waitcnt vmcnt(10)
	s_barrier
	s_waitcnt lgkmcnt(0)
	s_waitcnt lgkmcnt(0)
	v_mfma_f32_16x16x32_bf16 v[120:123], v[216:219], v[170:173], v[120:123]
	v_mfma_f32_16x16x32_bf16 v[112:115], v[224:227], v[170:173], v[112:115]
	v_mfma_f32_16x16x32_bf16 v[104:107], v[216:219], v[192:195], v[104:107]
	v_mfma_f32_16x16x32_bf16 v[96:99], v[224:227], v[192:195], v[96:99]
	v_mfma_f32_16x16x32_bf16 v[88:91], v[216:219], v[200:203], v[88:91]
	v_mfma_f32_16x16x32_bf16 v[80:83], v[224:227], v[200:203], v[80:83]
	v_mfma_f32_16x16x32_bf16 v[72:75], v[216:219], v[208:211], v[72:75]
	v_mfma_f32_16x16x32_bf16 v[64:67], v[224:227], v[208:211], v[64:67]
	v_mfma_f32_16x16x32_bf16 v[120:123], v[220:223], v[174:177], v[120:123]
	v_mfma_f32_16x16x32_bf16 v[112:115], v[228:231], v[174:177], v[112:115]
	v_mfma_f32_16x16x32_bf16 v[104:107], v[220:223], v[196:199], v[104:107]
	v_mfma_f32_16x16x32_bf16 v[96:99], v[228:231], v[196:199], v[96:99]
	v_mfma_f32_16x16x32_bf16 v[88:91], v[220:223], v[204:207], v[88:91]
	v_mfma_f32_16x16x32_bf16 v[80:83], v[228:231], v[204:207], v[80:83]
	v_mfma_f32_16x16x32_bf16 v[72:75], v[220:223], v[212:215], v[72:75]
	v_mfma_f32_16x16x32_bf16 v[64:67], v[228:231], v[212:215], v[64:67]
	s_mov_b32 m0, s55
	s_barrier
	ds_read_b128 v[170:173], v182 offset:49152
	ds_read_b128 v[174:177], v182 offset:50176
	ds_read_b128 v[192:195], v182 offset:51200
	ds_read_b128 v[196:199], v182 offset:52224
	ds_read_b128 v[200:203], v182 offset:53248
	ds_read_b128 v[204:207], v182 offset:54272
	ds_read_b128 v[208:211], v182 offset:55296
	ds_read_b128 v[212:215], v182 offset:56320
	global_load_lds_dwordx4 v142, s[82:83]
	s_mov_b32 m0, s56
	s_nop 0
	global_load_lds_dwordx4 v146, s[82:83]
	s_barrier
	s_waitcnt lgkmcnt(0)
	s_waitcnt lgkmcnt(0)
	v_mfma_f32_16x16x32_bf16 v[60:63], v[128:131], v[170:173], v[60:63]
	v_mfma_f32_16x16x32_bf16 v[52:55], v[136:139], v[170:173], v[52:55]
	v_mfma_f32_16x16x32_bf16 v[44:47], v[128:131], v[192:195], v[44:47]
	v_mfma_f32_16x16x32_bf16 v[36:39], v[136:139], v[192:195], v[36:39]
	v_mfma_f32_16x16x32_bf16 v[28:31], v[128:131], v[200:203], v[28:31]
	v_mfma_f32_16x16x32_bf16 v[20:23], v[136:139], v[200:203], v[20:23]
	v_mfma_f32_16x16x32_bf16 v[12:15], v[128:131], v[208:211], v[12:15]
	v_mfma_f32_16x16x32_bf16 v[4:7], v[136:139], v[208:211], v[4:7]
	v_mfma_f32_16x16x32_bf16 v[60:63], v[132:135], v[174:177], v[60:63]
	v_mfma_f32_16x16x32_bf16 v[52:55], v[166:169], v[174:177], v[52:55]
	v_mfma_f32_16x16x32_bf16 v[44:47], v[132:135], v[196:199], v[44:47]
	v_mfma_f32_16x16x32_bf16 v[36:39], v[166:169], v[196:199], v[36:39]
	v_mfma_f32_16x16x32_bf16 v[28:31], v[132:135], v[204:207], v[28:31]
	v_mfma_f32_16x16x32_bf16 v[20:23], v[166:169], v[204:207], v[20:23]
	v_mfma_f32_16x16x32_bf16 v[12:15], v[132:135], v[212:215], v[12:15]
	v_mfma_f32_16x16x32_bf16 v[4:7], v[166:169], v[212:215], v[4:7]
	s_barrier
	s_add_u32 s38, s38, 0x40080
	s_addc_u32 s39, s39, 0
	s_add_i32 s40, s40, s46
	s_mov_b32 m0, s40
	s_nop 0
	global_load_lds_dwordx4 v144, s[38:39]
	s_add_i32 m0, s40, 0x2000
	s_nop 0
	global_load_lds_dwordx4 v148, s[38:39]
	s_waitcnt vmcnt(10)
	s_barrier
	v_mfma_f32_16x16x32_bf16 v[56:59], v[216:219], v[170:173], v[56:59]
	v_mfma_f32_16x16x32_bf16 v[48:51], v[224:227], v[170:173], v[48:51]
	v_mfma_f32_16x16x32_bf16 v[40:43], v[216:219], v[192:195], v[40:43]
	v_mfma_f32_16x16x32_bf16 v[32:35], v[224:227], v[192:195], v[32:35]
	v_mfma_f32_16x16x32_bf16 v[24:27], v[216:219], v[200:203], v[24:27]
	v_mfma_f32_16x16x32_bf16 v[16:19], v[224:227], v[200:203], v[16:19]
	v_mfma_f32_16x16x32_bf16 v[8:11], v[216:219], v[208:211], v[8:11]
	v_mfma_f32_16x16x32_bf16 v[0:3], v[224:227], v[208:211], v[0:3]
	v_mfma_f32_16x16x32_bf16 v[56:59], v[220:223], v[174:177], v[56:59]
	v_mfma_f32_16x16x32_bf16 v[48:51], v[228:231], v[174:177], v[48:51]
	v_mfma_f32_16x16x32_bf16 v[40:43], v[220:223], v[196:199], v[40:43]
	v_mfma_f32_16x16x32_bf16 v[32:35], v[228:231], v[196:199], v[32:35]
	v_mfma_f32_16x16x32_bf16 v[24:27], v[220:223], v[204:207], v[24:27]
	v_mfma_f32_16x16x32_bf16 v[16:19], v[228:231], v[204:207], v[16:19]
	v_mfma_f32_16x16x32_bf16 v[8:11], v[220:223], v[212:215], v[8:11]
	v_mfma_f32_16x16x32_bf16 v[0:3], v[228:231], v[212:215], v[0:3]
	s_add_i32 s75, s75, 2
	s_add_u32 s8, s8, 0x100
	s_addc_u32 s9, s9, 0
	s_add_u32 s73, s73, 0x100
	s_addc_u32 s74, s74, 0
	s_cmp_gt_u32 s75, 13
	s_barrier
	s_cbranch_scc0 .LBB0_359
	s_setprio 0
	s_cmpk_gt_u32 s45, 0xff
	s_cbranch_scc1 .Lg359_nox
	s_barrier
	s_setprio 1

.Lg786_noy:
	ds_read_b128 v[144:147], v151
	ds_read_b128 v[156:159], v151 offset:1024
	ds_read_b128 v[160:163], v151 offset:2048
	ds_read_b128 v[164:167], v151 offset:3072
	s_add_u32 s30, s28, 0xfffc0080
	s_addc_u32 s31, s29, -1
	s_cmp_eq_u32 s61, 12
	s_cselect_b32 s35, s19, s31
	s_cselect_b32 s34, s57, s30
	s_cselect_b32 s31, s17, s60
	s_cselect_b32 s30, s58, s59
	s_add_i32 m0, s45, 0xc000
	ds_read_b128 v[168:171], v152
	ds_read_b128 v[172:175], v152 offset:1024
	ds_read_b128 v[176:179], v152 offset:2048
	ds_read_b128 v[180:183], v152 offset:3072
	ds_read_b128 v[184:187], v152 offset:4096
	ds_read_b128 v[188:191], v152 offset:5120
	ds_read_b128 v[192:195], v152 offset:6144
	ds_read_b128 v[196:199], v152 offset:7168
	global_load_lds_dwordx4 v136, s[28:29]
	s_add_i32 m0, s45, 0xe000
	s_nop 0
	global_load_lds_dwordx4 v138, s[28:29]
	s_waitcnt lgkmcnt(8)
	s_waitcnt vmcnt(10)
	s_barrier
	s_waitcnt lgkmcnt(0)
	s_waitcnt lgkmcnt(0)
	v_mfma_f32_16x16x32_bf16 v[124:127], v[144:147], v[168:171], 0
	v_mfma_f32_16x16x32_bf16 v[120:123], v[160:163], v[168:171], 0
	v_mfma_f32_16x16x32_bf16 v[108:111], v[144:147], v[176:179], 0
	v_mfma_f32_16x16x32_bf16 v[104:107], v[160:163], v[176:179], 0
	v_mfma_f32_16x16x32_bf16 v[92:95], v[144:147], v[184:187], 0
	v_mfma_f32_16x16x32_bf16 v[88:91], v[160:163], v[184:187], 0
	v_mfma_f32_16x16x32_bf16 v[76:79], v[144:147], v[192:195], 0
	v_mfma_f32_16x16x32_bf16 v[72:75], v[160:163], v[192:195], 0
	v_mfma_f32_16x16x32_bf16 v[124:127], v[156:159], v[172:175], v[124:127]
	v_mfma_f32_16x16x32_bf16 v[120:123], v[164:167], v[172:175], v[120:123]
	v_mfma_f32_16x16x32_bf16 v[108:111], v[156:159], v[180:183], v[108:111]
	v_mfma_f32_16x16x32_bf16 v[104:107], v[164:167], v[180:183], v[104:107]
	v_mfma_f32_16x16x32_bf16 v[92:95], v[156:159], v[188:191], v[92:95]
	v_mfma_f32_16x16x32_bf16 v[88:91], v[164:167], v[188:191], v[88:91]
	v_mfma_f32_16x16x32_bf16 v[76:79], v[156:159], v[196:199], v[76:79]
	v_mfma_f32_16x16x32_bf16 v[72:75], v[164:167], v[196:199], v[72:75]
	s_barrier
	s_add_i32 s62, s53, s42
	s_add_u32 s80, s30, 0x80
	s_addc_u32 s81, s31, 0
	s_mov_b32 m0, s62
	ds_read_b128 v[200:203], v153
	ds_read_b128 v[204:207], v153 offset:1024
	ds_read_b128 v[208:211], v153 offset:2048
	ds_read_b128 v[212:215], v153 offset:3072
	global_load_lds_dwordx4 v132, s[30:31]
	s_add_i32 m0, s62, 0x2000
	s_nop 0
	global_load_lds_dwordx4 v128, s[30:31]
	s_waitcnt vmcnt(10)
	s_barrier
	s_waitcnt lgkmcnt(0)
	s_waitcnt lgkmcnt(0)
	v_mfma_f32_16x16x32_bf16 v[116:119], v[200:203], v[168:171], 0
	v_mfma_f32_16x16x32_bf16 v[112:115], v[208:211], v[168:171], 0
	v_mfma_f32_16x16x32_bf16 v[100:103], v[200:203], v[176:179], 0
	v_mfma_f32_16x16x32_bf16 v[96:99], v[208:211], v[176:179], 0
	v_mfma_f32_16x16x32_bf16 v[84:87], v[200:203], v[184:187], 0
	v_mfma_f32_16x16x32_bf16 v[80:83], v[208:211], v[184:187], 0
	v_mfma_f32_16x16x32_bf16 v[68:71], v[200:203], v[192:195], 0
	v_mfma_f32_16x16x32_bf16 v[64:67], v[208:211], v[192:195], 0
	v_mfma_f32_16x16x32_bf16 v[116:119], v[204:207], v[172:175], v[116:119]
	v_mfma_f32_16x16x32_bf16 v[112:115], v[212:215], v[172:175], v[112:115]
	v_mfma_f32_16x16x32_bf16 v[100:103], v[204:207], v[180:183], v[100:103]
	v_mfma_f32_16x16x32_bf16 v[96:99], v[212:215], v[180:183], v[96:99]
	v_mfma_f32_16x16x32_bf16 v[84:87], v[204:207], v[188:191], v[84:87]
	v_mfma_f32_16x16x32_bf16 v[80:83], v[212:215], v[188:191], v[80:83]
	v_mfma_f32_16x16x32_bf16 v[68:71], v[204:207], v[196:199], v[68:71]
	v_mfma_f32_16x16x32_bf16 v[64:67], v[212:215], v[196:199], v[64:67]
	s_mov_b32 m0, s45
	s_add_u32 s82, s34, 0x80
	s_addc_u32 s83, s35, 0
	s_barrier
	ds_read_b128 v[168:171], v152 offset:16384
	ds_read_b128 v[172:175], v152 offset:17408
	ds_read_b128 v[176:179], v152 offset:18432
	ds_read_b128 v[180:183], v152 offset:19456
	ds_read_b128 v[184:187], v152 offset:20480
	ds_read_b128 v[188:191], v152 offset:21504
	ds_read_b128 v[192:195], v152 offset:22528
	ds_read_b128 v[196:199], v152 offset:23552
	global_load_lds_dwordx4 v134, s[34:35]
	s_mov_b32 m0, s46
	s_nop 0
	global_load_lds_dwordx4 v130, s[34:35]
	s_barrier
	s_waitcnt lgkmcnt(0)
	s_waitcnt lgkmcnt(0)
	v_mfma_f32_16x16x32_bf16 v[60:63], v[144:147], v[168:171], 0
	v_mfma_f32_16x16x32_bf16 v[56:59], v[160:163], v[168:171], 0
	v_mfma_f32_16x16x32_bf16 v[44:47], v[144:147], v[176:179], 0
	v_mfma_f32_16x16x32_bf16 v[40:43], v[160:163], v[176:179], 0
	v_mfma_f32_16x16x32_bf16 v[28:31], v[144:147], v[184:187], 0
	v_mfma_f32_16x16x32_bf16 v[24:27], v[160:163], v[184:187], 0
	v_mfma_f32_16x16x32_bf16 v[12:15], v[144:147], v[192:195], 0
	v_mfma_f32_16x16x32_bf16 v[8:11], v[160:163], v[192:195], 0
	v_mfma_f32_16x16x32_bf16 v[60:63], v[156:159], v[172:175], v[60:63]
	v_mfma_f32_16x16x32_bf16 v[56:59], v[164:167], v[172:175], v[56:59]
	v_mfma_f32_16x16x32_bf16 v[44:47], v[156:159], v[180:183], v[44:47]
	v_mfma_f32_16x16x32_bf16 v[40:43], v[164:167], v[180:183], v[40:43]
	v_mfma_f32_16x16x32_bf16 v[28:31], v[156:159], v[188:191], v[28:31]
	v_mfma_f32_16x16x32_bf16 v[24:27], v[164:167], v[188:191], v[24:27]
	v_mfma_f32_16x16x32_bf16 v[12:15], v[156:159], v[196:199], v[12:15]
	v_mfma_f32_16x16x32_bf16 v[8:11], v[164:167], v[196:199], v[8:11]
	s_barrier
	s_add_u32 s62, s30, 0x40000
	s_addc_u32 s63, s31, 0
	s_add_i32 s64, s54, s42
	s_mov_b32 m0, s64
	s_nop 0
	global_load_lds_dwordx4 v132, s[62:63]
	s_add_i32 m0, s64, 0x2000
	s_nop 0
	global_load_lds_dwordx4 v128, s[62:63]
	s_waitcnt vmcnt(10)
	s_barrier
	v_mfma_f32_16x16x32_bf16 v[52:55], v[200:203], v[168:171], 0
	v_mfma_f32_16x16x32_bf16 v[48:51], v[208:211], v[168:171], 0
	v_mfma_f32_16x16x32_bf16 v[36:39], v[200:203], v[176:179], 0
	v_mfma_f32_16x16x32_bf16 v[32:35], v[208:211], v[176:179], 0
	v_mfma_f32_16x16x32_bf16 v[20:23], v[200:203], v[184:187], 0
	v_mfma_f32_16x16x32_bf16 v[16:19], v[208:211], v[184:187], 0
	v_mfma_f32_16x16x32_bf16 v[4:7], v[200:203], v[192:195], 0
	v_mfma_f32_16x16x32_bf16 v[0:3], v[208:211], v[192:195], 0
	v_mfma_f32_16x16x32_bf16 v[52:55], v[204:207], v[172:175], v[52:55]
	v_mfma_f32_16x16x32_bf16 v[48:51], v[212:215], v[172:175], v[48:51]
	v_mfma_f32_16x16x32_bf16 v[36:39], v[204:207], v[180:183], v[36:39]
	v_mfma_f32_16x16x32_bf16 v[32:35], v[212:215], v[180:183], v[32:35]
	v_mfma_f32_16x16x32_bf16 v[20:23], v[204:207], v[188:191], v[20:23]
	v_mfma_f32_16x16x32_bf16 v[16:19], v[212:215], v[188:191], v[16:19]
	v_mfma_f32_16x16x32_bf16 v[4:7], v[204:207], v[196:199], v[4:7]
	v_mfma_f32_16x16x32_bf16 v[0:3], v[212:215], v[196:199], v[0:3]
	s_add_i32 s62, 0, 0x18000
	v_add_u32_e32 v155, s62, v149
	s_barrier
	s_branch .Lg786_mid
.LBB0_786:
	ds_read_b128 v[144:147], v151
	ds_read_b128 v[156:159], v151 offset:1024
	ds_read_b128 v[160:163], v151 offset:2048
	ds_read_b128 v[164:167], v151 offset:3072
	s_add_u32 s30, s28, 0xfffc0080
	s_addc_u32 s31, s29, -1
	s_cmp_eq_u32 s61, 12
	s_cselect_b32 s35, s19, s31
	s_cselect_b32 s34, s57, s30
	s_cselect_b32 s31, s17, s60
	s_cselect_b32 s30, s58, s59
	s_add_i32 m0, s45, 0xc000
	ds_read_b128 v[168:171], v152
	ds_read_b128 v[172:175], v152 offset:1024
	ds_read_b128 v[176:179], v152 offset:2048
	ds_read_b128 v[180:183], v152 offset:3072
	ds_read_b128 v[184:187], v152 offset:4096
	ds_read_b128 v[188:191], v152 offset:5120
	ds_read_b128 v[192:195], v152 offset:6144
	ds_read_b128 v[196:199], v152 offset:7168
	global_load_lds_dwordx4 v136, s[28:29]
	s_add_i32 m0, s45, 0xe000
	s_nop 0
	global_load_lds_dwordx4 v138, s[28:29]
	s_waitcnt lgkmcnt(8)
	s_waitcnt vmcnt(10)
	s_barrier
	s_waitcnt lgkmcnt(0)
	s_waitcnt lgkmcnt(0)
	v_mfma_f32_16x16x32_bf16 v[124:127], v[144:147], v[168:171], v[124:127]
	v_mfma_f32_16x16x32_bf16 v[120:123], v[160:163], v[168:171], v[120:123]
	v_mfma_f32_16x16x32_bf16 v[108:111], v[144:147], v[176:179], v[108:111]
	v_mfma_f32_16x16x32_bf16 v[104:107], v[160:163], v[176:179], v[104:107]
	v_mfma_f32_16x16x32_bf16 v[92:95], v[144:147], v[184:187], v[92:95]
	v_mfma_f32_16x16x32_bf16 v[88:91], v[160:163], v[184:187], v[88:91]
	v_mfma_f32_16x16x32_bf16 v[76:79], v[144:147], v[192:195], v[76:79]
	v_mfma_f32_16x16x32_bf16 v[72:75], v[160:163], v[192:195], v[72:75]
	v_mfma_f32_16x16x32_bf16 v[124:127], v[156:159], v[172:175], v[124:127]
	v_mfma_f32_16x16x32_bf16 v[120:123], v[164:167], v[172:175], v[120:123]
	v_mfma_f32_16x16x32_bf16 v[108:111], v[156:159], v[180:183], v[108:111]
	v_mfma_f32_16x16x32_bf16 v[104:107], v[164:167], v[180:183], v[104:107]
	v_mfma_f32_16x16x32_bf16 v[92:95], v[156:159], v[188:191], v[92:95]
	v_mfma_f32_16x16x32_bf16 v[88:91], v[164:167], v[188:191], v[88:91]
	v_mfma_f32_16x16x32_bf16 v[76:79], v[156:159], v[196:199], v[76:79]
	v_mfma_f32_16x16x32_bf16 v[72:75], v[164:167], v[196:199], v[72:75]
	s_barrier
	s_add_i32 s62, s53, s42
	s_add_u32 s80, s30, 0x80
	s_addc_u32 s81, s31, 0
	s_mov_b32 m0, s62
	ds_read_b128 v[200:203], v153
	ds_read_b128 v[204:207], v153 offset:1024
	ds_read_b128 v[208:211], v153 offset:2048
	ds_read_b128 v[212:215], v153 offset:3072
	global_load_lds_dwordx4 v132, s[30:31]
	s_add_i32 m0, s62, 0x2000
	s_nop 0
	global_load_lds_dwordx4 v128, s[30:31]
	s_waitcnt vmcnt(10)
	s_barrier
	s_waitcnt lgkmcnt(0)
	s_waitcnt lgkmcnt(0)
	v_mfma_f32_16x16x32_bf16 v[116:119], v[200:203], v[168:171], v[116:119]
	v_mfma_f32_16x16x32_bf16 v[112:115], v[208:211], v[168:171], v[112:115]
	v_mfma_f32_16x16x32_bf16 v[100:103], v[200:203], v[176:179], v[100:103]
	v_mfma_f32_16x16x32_bf16 v[96:99], v[208:211], v[176:179], v[96:99]
	v_mfma_f32_16x16x32_bf16 v[84:87], v[200:203], v[184:187], v[84:87]
	v_mfma_f32_16x16x32_bf16 v[80:83], v[208:211], v[184:187], v[80:83]
	v_mfma_f32_16x16x32_bf16 v[68:71], v[200:203], v[192:195], v[68:71]
	v_mfma_f32_16x16x32_bf16 v[64:67], v[208:211], v[192:195], v[64:67]
	v_mfma_f32_16x16x32_bf16 v[116:119], v[204:207], v[172:175], v[116:119]
	v_mfma_f32_16x16x32_bf16 v[112:115], v[212:215], v[172:175], v[112:115]
	v_mfma_f32_16x16x32_bf16 v[100:103], v[204:207], v[180:183], v[100:103]
	v_mfma_f32_16x16x32_bf16 v[96:99], v[212:215], v[180:183], v[96:99]
	v_mfma_f32_16x16x32_bf16 v[84:87], v[204:207], v[188:191], v[84:87]
	v_mfma_f32_16x16x32_bf16 v[80:83], v[212:215], v[188:191], v[80:83]
	v_mfma_f32_16x16x32_bf16 v[68:71], v[204:207], v[196:199], v[68:71]
	v_mfma_f32_16x16x32_bf16 v[64:67], v[212:215], v[196:199], v[64:67]
	s_mov_b32 m0, s45
	s_add_u32 s82, s34, 0x80
	s_addc_u32 s83, s35, 0
	s_barrier
	ds_read_b128 v[168:171], v152 offset:16384
	ds_read_b128 v[172:175], v152 offset:17408
	ds_read_b128 v[176:179], v152 offset:18432
	ds_read_b128 v[180:183], v152 offset:19456
	ds_read_b128 v[184:187], v152 offset:20480
	ds_read_b128 v[188:191], v152 offset:21504
	ds_read_b128 v[192:195], v152 offset:22528
	ds_read_b128 v[196:199], v152 offset:23552
	global_load_lds_dwordx4 v134, s[34:35]
	s_mov_b32 m0, s46
	s_nop 0
	global_load_lds_dwordx4 v130, s[34:35]
	s_barrier
	s_waitcnt lgkmcnt(0)
	s_waitcnt lgkmcnt(0)
	v_mfma_f32_16x16x32_bf16 v[60:63], v[144:147], v[168:171], v[60:63]
	v_mfma_f32_16x16x32_bf16 v[56:59], v[160:163], v[168:171], v[56:59]
	v_mfma_f32_16x16x32_bf16 v[44:47], v[144:147], v[176:179], v[44:47]
	v_mfma_f32_16x16x32_bf16 v[40:43], v[160:163], v[176:179], v[40:43]
	v_mfma_f32_16x16x32_bf16 v[28:31], v[144:147], v[184:187], v[28:31]
	v_mfma_f32_16x16x32_bf16 v[24:27], v[160:163], v[184:187], v[24:27]
	v_mfma_f32_16x16x32_bf16 v[12:15], v[144:147], v[192:195], v[12:15]
	v_mfma_f32_16x16x32_bf16 v[8:11], v[160:163], v[192:195], v[8:11]
	v_mfma_f32_16x16x32_bf16 v[60:63], v[156:159], v[172:175], v[60:63]
	v_mfma_f32_16x16x32_bf16 v[56:59], v[164:167], v[172:175], v[56:59]
	v_mfma_f32_16x16x32_bf16 v[44:47], v[156:159], v[180:183], v[44:47]
	v_mfma_f32_16x16x32_bf16 v[40:43], v[164:167], v[180:183], v[40:43]
	v_mfma_f32_16x16x32_bf16 v[28:31], v[156:159], v[188:191], v[28:31]
	v_mfma_f32_16x16x32_bf16 v[24:27], v[164:167], v[188:191], v[24:27]
	v_mfma_f32_16x16x32_bf16 v[12:15], v[156:159], v[196:199], v[12:15]
	v_mfma_f32_16x16x32_bf16 v[8:11], v[164:167], v[196:199], v[8:11]
	s_barrier
	s_add_u32 s62, s30, 0x40000
	s_addc_u32 s63, s31, 0
	s_add_i32 s64, s54, s42
	s_mov_b32 m0, s64
	s_nop 0
	global_load_lds_dwordx4 v132, s[62:63]
	s_add_i32 m0, s64, 0x2000
	s_nop 0
	global_load_lds_dwordx4 v128, s[62:63]
	s_waitcnt vmcnt(10)
	s_barrier
	v_mfma_f32_16x16x32_bf16 v[52:55], v[200:203], v[168:171], v[52:55]
	v_mfma_f32_16x16x32_bf16 v[48:51], v[208:211], v[168:171], v[48:51]
	v_mfma_f32_16x16x32_bf16 v[36:39], v[200:203], v[176:179], v[36:39]
	v_mfma_f32_16x16x32_bf16 v[32:35], v[208:211], v[176:179], v[32:35]
	v_mfma_f32_16x16x32_bf16 v[20:23], v[200:203], v[184:187], v[20:23]
	v_mfma_f32_16x16x32_bf16 v[16:19], v[208:211], v[184:187], v[16:19]
	v_mfma_f32_16x16x32_bf16 v[4:7], v[200:203], v[192:195], v[4:7]
	v_mfma_f32_16x16x32_bf16 v[0:3], v[208:211], v[192:195], v[0:3]
	v_mfma_f32_16x16x32_bf16 v[52:55], v[204:207], v[172:175], v[52:55]
	v_mfma_f32_16x16x32_bf16 v[48:51], v[212:215], v[172:175], v[48:51]
	v_mfma_f32_16x16x32_bf16 v[36:39], v[204:207], v[180:183], v[36:39]
	v_mfma_f32_16x16x32_bf16 v[32:35], v[212:215], v[180:183], v[32:35]
	v_mfma_f32_16x16x32_bf16 v[20:23], v[204:207], v[188:191], v[20:23]
	v_mfma_f32_16x16x32_bf16 v[16:19], v[212:215], v[188:191], v[16:19]
	v_mfma_f32_16x16x32_bf16 v[4:7], v[204:207], v[196:199], v[4:7]
	v_mfma_f32_16x16x32_bf16 v[0:3], v[212:215], v[196:199], v[0:3]
	s_add_i32 s62, 0, 0x18000
	v_add_u32_e32 v155, s62, v149
	s_barrier
.Lg786_mid:
	ds_read_b128 v[144:147], v155
	ds_read_b128 v[156:159], v155 offset:1024
	ds_read_b128 v[160:163], v155 offset:2048
	ds_read_b128 v[164:167], v155 offset:3072
	s_add_u32 s34, s34, 0x40000
	s_addc_u32 s35, s35, 0
	s_mov_b32 m0, s47
	ds_read_b128 v[168:171], v152 offset:32768
	ds_read_b128 v[172:175], v152 offset:33792
	ds_read_b128 v[176:179], v152 offset:34816
	ds_read_b128 v[180:183], v152 offset:35840
	ds_read_b128 v[184:187], v152 offset:36864
	ds_read_b128 v[188:191], v152 offset:37888
	ds_read_b128 v[192:195], v152 offset:38912
	ds_read_b128 v[196:199], v152 offset:39936
	global_load_lds_dwordx4 v134, s[34:35]
	s_mov_b32 m0, s48
	s_nop 0
	global_load_lds_dwordx4 v130, s[34:35]
	s_waitcnt lgkmcnt(8)
	s_waitcnt vmcnt(10)
	s_barrier
	s_waitcnt lgkmcnt(0)
	s_waitcnt lgkmcnt(0)
	v_mfma_f32_16x16x32_bf16 v[124:127], v[144:147], v[168:171], v[124:127]
	v_mfma_f32_16x16x32_bf16 v[120:123], v[160:163], v[168:171], v[120:123]
	v_mfma_f32_16x16x32_bf16 v[108:111], v[144:147], v[176:179], v[108:111]
	v_mfma_f32_16x16x32_bf16 v[104:107], v[160:163], v[176:179], v[104:107]
	v_mfma_f32_16x16x32_bf16 v[92:95], v[144:147], v[184:187], v[92:95]
	v_mfma_f32_16x16x32_bf16 v[88:91], v[160:163], v[184:187], v[88:91]
	v_mfma_f32_16x16x32_bf16 v[76:79], v[144:147], v[192:195], v[76:79]
	v_mfma_f32_16x16x32_bf16 v[72:75], v[160:163], v[192:195], v[72:75]
	v_mfma_f32_16x16x32_bf16 v[124:127], v[156:159], v[172:175], v[124:127]
	v_mfma_f32_16x16x32_bf16 v[120:123], v[164:167], v[172:175], v[120:123]
	v_mfma_f32_16x16x32_bf16 v[108:111], v[156:159], v[180:183], v[108:111]
	v_mfma_f32_16x16x32_bf16 v[104:107], v[164:167], v[180:183], v[104:107]
	v_mfma_f32_16x16x32_bf16 v[92:95], v[156:159], v[188:191], v[92:95]
	v_mfma_f32_16x16x32_bf16 v[88:91], v[164:167], v[188:191], v[88:91]
	v_mfma_f32_16x16x32_bf16 v[76:79], v[156:159], v[196:199], v[76:79]
	v_mfma_f32_16x16x32_bf16 v[72:75], v[164:167], v[196:199], v[72:75]
	s_barrier
	s_add_i32 s34, 0, 0x1c000
	s_add_i32 s35, s62, s42
	v_add_u32_e32 v155, s34, v149
	s_mov_b32 m0, s35
	ds_read_b128 v[200:203], v155
	ds_read_b128 v[204:207], v155 offset:1024
	ds_read_b128 v[208:211], v155 offset:2048
	ds_read_b128 v[212:215], v155 offset:3072
	global_load_lds_dwordx4 v132, s[80:81]
	s_add_i32 m0, s35, 0x2000
	s_nop 0
	global_load_lds_dwordx4 v128, s[80:81]
	s_waitcnt vmcnt(10)
	s_barrier
	s_waitcnt lgkmcnt(0)
	s_waitcnt lgkmcnt(0)
	v_mfma_f32_16x16x32_bf16 v[116:119], v[200:203], v[168:171], v[116:119]
	v_mfma_f32_16x16x32_bf16 v[112:115], v[208:211], v[168:171], v[112:115]
	v_mfma_f32_16x16x32_bf16 v[100:103], v[200:203], v[176:179], v[100:103]
	v_mfma_f32_16x16x32_bf16 v[96:99], v[208:211], v[176:179], v[96:99]
	v_mfma_f32_16x16x32_bf16 v[84:87], v[200:203], v[184:187], v[84:87]
	v_mfma_f32_16x16x32_bf16 v[80:83], v[208:211], v[184:187], v[80:83]
	v_mfma_f32_16x16x32_bf16 v[68:71], v[200:203], v[192:195], v[68:71]
	v_mfma_f32_16x16x32_bf16 v[64:67], v[208:211], v[192:195], v[64:67]
	v_mfma_f32_16x16x32_bf16 v[116:119], v[204:207], v[172:175], v[116:119]
	v_mfma_f32_16x16x32_bf16 v[112:115], v[212:215], v[172:175], v[112:115]
	v_mfma_f32_16x16x32_bf16 v[100:103], v[204:207], v[180:183], v[100:103]
	v_mfma_f32_16x16x32_bf16 v[96:99], v[212:215], v[180:183], v[96:99]
	v_mfma_f32_16x16x32_bf16 v[84:87], v[204:207], v[188:191], v[84:87]
	v_mfma_f32_16x16x32_bf16 v[80:83], v[212:215], v[188:191], v[80:83]
	v_mfma_f32_16x16x32_bf16 v[68:71], v[204:207], v[196:199], v[68:71]
	v_mfma_f32_16x16x32_bf16 v[64:67], v[212:215], v[196:199], v[64:67]
	s_mov_b32 m0, s50
	s_barrier
	ds_read_b128 v[168:171], v152 offset:49152
	ds_read_b128 v[172:175], v152 offset:50176
	ds_read_b128 v[176:179], v152 offset:51200
	ds_read_b128 v[180:183], v152 offset:52224
	ds_read_b128 v[184:187], v152 offset:53248
	ds_read_b128 v[188:191], v152 offset:54272
	ds_read_b128 v[192:195], v152 offset:55296
	ds_read_b128 v[196:199], v152 offset:56320
	global_load_lds_dwordx4 v134, s[82:83]
	s_mov_b32 m0, s51
	s_nop 0
	global_load_lds_dwordx4 v130, s[82:83]
	s_barrier
	s_waitcnt lgkmcnt(0)
	s_waitcnt lgkmcnt(0)
	v_mfma_f32_16x16x32_bf16 v[60:63], v[144:147], v[168:171], v[60:63]
	v_mfma_f32_16x16x32_bf16 v[56:59], v[160:163], v[168:171], v[56:59]
	v_mfma_f32_16x16x32_bf16 v[44:47], v[144:147], v[176:179], v[44:47]
	v_mfma_f32_16x16x32_bf16 v[40:43], v[160:163], v[176:179], v[40:43]
	v_mfma_f32_16x16x32_bf16 v[28:31], v[144:147], v[184:187], v[28:31]
	v_mfma_f32_16x16x32_bf16 v[24:27], v[160:163], v[184:187], v[24:27]
	v_mfma_f32_16x16x32_bf16 v[12:15], v[144:147], v[192:195], v[12:15]
	v_mfma_f32_16x16x32_bf16 v[8:11], v[160:163], v[192:195], v[8:11]
	v_mfma_f32_16x16x32_bf16 v[60:63], v[156:159], v[172:175], v[60:63]
	v_mfma_f32_16x16x32_bf16 v[56:59], v[164:167], v[172:175], v[56:59]
	v_mfma_f32_16x16x32_bf16 v[44:47], v[156:159], v[180:183], v[44:47]
	v_mfma_f32_16x16x32_bf16 v[40:43], v[164:167], v[180:183], v[40:43]
	v_mfma_f32_16x16x32_bf16 v[28:31], v[156:159], v[188:191], v[28:31]
	v_mfma_f32_16x16x32_bf16 v[24:27], v[164:167], v[188:191], v[24:27]
	v_mfma_f32_16x16x32_bf16 v[12:15], v[156:159], v[196:199], v[12:15]
	v_mfma_f32_16x16x32_bf16 v[8:11], v[164:167], v[196:199], v[8:11]
	s_barrier
	s_add_u32 s30, s30, 0x40080
	s_addc_u32 s31, s31, 0
	s_add_i32 s34, s34, s42
	s_mov_b32 m0, s34
	s_nop 0
	global_load_lds_dwordx4 v132, s[30:31]
	s_add_i32 m0, s34, 0x2000
	s_nop 0
	global_load_lds_dwordx4 v128, s[30:31]
	s_waitcnt vmcnt(10)
	s_barrier
	v_mfma_f32_16x16x32_bf16 v[52:55], v[200:203], v[168:171], v[52:55]
	v_mfma_f32_16x16x32_bf16 v[48:51], v[208:211], v[168:171], v[48:51]
	v_mfma_f32_16x16x32_bf16 v[36:39], v[200:203], v[176:179], v[36:39]
	v_mfma_f32_16x16x32_bf16 v[32:35], v[208:211], v[176:179], v[32:35]
	v_mfma_f32_16x16x32_bf16 v[20:23], v[200:203], v[184:187], v[20:23]
	v_mfma_f32_16x16x32_bf16 v[16:19], v[208:211], v[184:187], v[16:19]
	v_mfma_f32_16x16x32_bf16 v[4:7], v[200:203], v[192:195], v[4:7]
	v_mfma_f32_16x16x32_bf16 v[0:3], v[208:211], v[192:195], v[0:3]
	v_mfma_f32_16x16x32_bf16 v[52:55], v[204:207], v[172:175], v[52:55]
	v_mfma_f32_16x16x32_bf16 v[48:51], v[212:215], v[172:175], v[48:51]
	v_mfma_f32_16x16x32_bf16 v[36:39], v[204:207], v[180:183], v[36:39]
	v_mfma_f32_16x16x32_bf16 v[32:35], v[212:215], v[180:183], v[32:35]
	v_mfma_f32_16x16x32_bf16 v[20:23], v[204:207], v[188:191], v[20:23]
	v_mfma_f32_16x16x32_bf16 v[16:19], v[212:215], v[188:191], v[16:19]
	v_mfma_f32_16x16x32_bf16 v[4:7], v[204:207], v[196:199], v[4:7]
	v_mfma_f32_16x16x32_bf16 v[0:3], v[212:215], v[196:199], v[0:3]
	s_add_i32 s61, s61, 2
	s_add_u32 s28, s28, 0x100
	s_addc_u32 s29, s29, 0
	s_add_u32 s59, s59, 0x100
	s_addc_u32 s60, s60, 0
	s_cmp_gt_u32 s61, 13
	s_barrier
	s_cbranch_scc0 .LBB0_786
	s_setprio 0
	v_lshl_add_u32 v146, s8, 8, v148
	v_ashrrev_i32_e32 v147, 31, v146
	v_lshl_or_b32 v144, s56, 8, v150
	v_lshlrev_b64 v[156:157], 11, v[146:147]
	v_ashrrev_i32_e32 v145, 31, v144
	v_lshl_add_u64 v[156:157], s[10:11], 0, v[156:157]
	v_lshl_add_u64 v[166:167], v[144:145], 1, v[156:157]
	global_load_dwordx4 v[158:161], v[166:167], off
	global_load_dwordx4 v[162:165], v[166:167], off offset:256
	s_mov_b64 s[84:85], 0x8000
	s_mov_b64 s[86:87], 0x28000
	v_lshl_add_u64 v[232:233], v[166:167], 0, s[84:85]
	global_load_dwordx4 v[176:179], v[232:233], off
	global_load_dwordx4 v[180:183], v[232:233], off offset:256
	v_lshl_add_u64 v[232:233], v[232:233], 0, s[84:85]
	global_load_dwordx4 v[184:187], v[232:233], off
	global_load_dwordx4 v[188:191], v[232:233], off offset:256
	v_lshl_add_u64 v[232:233], v[232:233], 0, s[84:85]
	global_load_dwordx4 v[192:195], v[232:233], off
	global_load_dwordx4 v[196:199], v[232:233], off offset:256
	v_lshl_add_u64 v[232:233], v[232:233], 0, s[86:87]
	global_load_dwordx4 v[200:203], v[232:233], off
	global_load_dwordx4 v[204:207], v[232:233], off offset:256
	v_lshl_add_u64 v[232:233], v[232:233], 0, s[84:85]
	global_load_dwordx4 v[208:211], v[232:233], off
	global_load_dwordx4 v[212:215], v[232:233], off offset:256
	v_lshl_add_u64 v[232:233], v[232:233], 0, s[84:85]
	global_load_dwordx4 v[216:219], v[232:233], off
	global_load_dwordx4 v[220:223], v[232:233], off offset:256
	v_lshl_add_u64 v[232:233], v[232:233], 0, s[84:85]
	global_load_dwordx4 v[224:227], v[232:233], off
	global_load_dwordx4 v[228:231], v[232:233], off offset:256
	s_cmpk_gt_u32 s37, 0xff
	s_cbranch_scc1 .Lg786_nox
	s_barrier
	s_setprio 1

.Lg893_noy:
	ds_read_b128 v[152:155], v148
	ds_read_b128 v[156:159], v148 offset:1024
	ds_read_b128 v[160:163], v148 offset:2048
	ds_read_b128 v[164:167], v148 offset:3072
	s_add_u32 s26, s20, 0xfffc0080
	s_addc_u32 s27, s21, -1
	s_cmp_eq_u32 s57, 12
	s_cselect_b32 s29, s13, s27
	s_cselect_b32 s28, s53, s26
	s_cselect_b32 s27, s11, s56
	s_cselect_b32 s26, s54, s55
	s_add_i32 m0, s19, 0xc000
	ds_read_b128 v[168:171], v149
	ds_read_b128 v[172:175], v149 offset:1024
	ds_read_b128 v[176:179], v149 offset:2048
	ds_read_b128 v[180:183], v149 offset:3072
	ds_read_b128 v[184:187], v149 offset:4096
	ds_read_b128 v[188:191], v149 offset:5120
	ds_read_b128 v[192:195], v149 offset:6144
	ds_read_b128 v[196:199], v149 offset:7168
	global_load_lds_dwordx4 v136, s[20:21]
	s_add_i32 m0, s19, 0xe000
	s_nop 0
	global_load_lds_dwordx4 v138, s[20:21]
	s_waitcnt lgkmcnt(8)
	s_waitcnt vmcnt(10)
	s_barrier
	s_waitcnt lgkmcnt(0)
	s_waitcnt lgkmcnt(0)
	v_mfma_f32_16x16x32_bf16 v[124:127], v[152:155], v[168:171], 0
	v_mfma_f32_16x16x32_bf16 v[120:123], v[160:163], v[168:171], 0
	v_mfma_f32_16x16x32_bf16 v[108:111], v[152:155], v[176:179], 0
	v_mfma_f32_16x16x32_bf16 v[104:107], v[160:163], v[176:179], 0
	v_mfma_f32_16x16x32_bf16 v[92:95], v[152:155], v[184:187], 0
	v_mfma_f32_16x16x32_bf16 v[88:91], v[160:163], v[184:187], 0
	v_mfma_f32_16x16x32_bf16 v[76:79], v[152:155], v[192:195], 0
	v_mfma_f32_16x16x32_bf16 v[72:75], v[160:163], v[192:195], 0
	v_mfma_f32_16x16x32_bf16 v[124:127], v[156:159], v[172:175], v[124:127]
	v_mfma_f32_16x16x32_bf16 v[120:123], v[164:167], v[172:175], v[120:123]
	v_mfma_f32_16x16x32_bf16 v[108:111], v[156:159], v[180:183], v[108:111]
	v_mfma_f32_16x16x32_bf16 v[104:107], v[164:167], v[180:183], v[104:107]
	v_mfma_f32_16x16x32_bf16 v[92:95], v[156:159], v[188:191], v[92:95]
	v_mfma_f32_16x16x32_bf16 v[88:91], v[164:167], v[188:191], v[88:91]
	v_mfma_f32_16x16x32_bf16 v[76:79], v[156:159], v[196:199], v[76:79]
	v_mfma_f32_16x16x32_bf16 v[72:75], v[164:167], v[196:199], v[72:75]
	s_barrier
	s_add_i32 s58, s47, s31
	s_add_u32 s80, s26, 0x80
	s_addc_u32 s81, s27, 0
	s_mov_b32 m0, s58
	ds_read_b128 v[200:203], v150
	ds_read_b128 v[204:207], v150 offset:1024
	ds_read_b128 v[208:211], v150 offset:2048
	ds_read_b128 v[212:215], v150 offset:3072
	global_load_lds_dwordx4 v132, s[26:27]
	s_add_i32 m0, s58, 0x2000
	s_nop 0
	global_load_lds_dwordx4 v128, s[26:27]
	s_waitcnt vmcnt(10)
	s_barrier
	s_waitcnt lgkmcnt(0)
	s_waitcnt lgkmcnt(0)
	v_mfma_f32_16x16x32_bf16 v[116:119], v[200:203], v[168:171], 0
	v_mfma_f32_16x16x32_bf16 v[112:115], v[208:211], v[168:171], 0
	v_mfma_f32_16x16x32_bf16 v[100:103], v[200:203], v[176:179], 0
	v_mfma_f32_16x16x32_bf16 v[96:99], v[208:211], v[176:179], 0
	v_mfma_f32_16x16x32_bf16 v[84:87], v[200:203], v[184:187], 0
	v_mfma_f32_16x16x32_bf16 v[80:83], v[208:211], v[184:187], 0
	v_mfma_f32_16x16x32_bf16 v[68:71], v[200:203], v[192:195], 0
	v_mfma_f32_16x16x32_bf16 v[64:67], v[208:211], v[192:195], 0
	v_mfma_f32_16x16x32_bf16 v[116:119], v[204:207], v[172:175], v[116:119]
	v_mfma_f32_16x16x32_bf16 v[112:115], v[212:215], v[172:175], v[112:115]
	v_mfma_f32_16x16x32_bf16 v[100:103], v[204:207], v[180:183], v[100:103]
	v_mfma_f32_16x16x32_bf16 v[96:99], v[212:215], v[180:183], v[96:99]
	v_mfma_f32_16x16x32_bf16 v[84:87], v[204:207], v[188:191], v[84:87]
	v_mfma_f32_16x16x32_bf16 v[80:83], v[212:215], v[188:191], v[80:83]
	v_mfma_f32_16x16x32_bf16 v[68:71], v[204:207], v[196:199], v[68:71]
	v_mfma_f32_16x16x32_bf16 v[64:67], v[212:215], v[196:199], v[64:67]
	s_mov_b32 m0, s19
	s_add_u32 s82, s28, 0x80
	s_addc_u32 s83, s29, 0
	s_barrier
	ds_read_b128 v[168:171], v149 offset:16384
	ds_read_b128 v[172:175], v149 offset:17408
	ds_read_b128 v[176:179], v149 offset:18432
	ds_read_b128 v[180:183], v149 offset:19456
	ds_read_b128 v[184:187], v149 offset:20480
	ds_read_b128 v[188:191], v149 offset:21504
	ds_read_b128 v[192:195], v149 offset:22528
	ds_read_b128 v[196:199], v149 offset:23552
	global_load_lds_dwordx4 v134, s[28:29]
	s_mov_b32 m0, s42
	s_nop 0
	global_load_lds_dwordx4 v130, s[28:29]
	s_barrier
	s_waitcnt lgkmcnt(0)
	s_waitcnt lgkmcnt(0)
	v_mfma_f32_16x16x32_bf16 v[60:63], v[152:155], v[168:171], 0
	v_mfma_f32_16x16x32_bf16 v[56:59], v[160:163], v[168:171], 0
	v_mfma_f32_16x16x32_bf16 v[44:47], v[152:155], v[176:179], 0
	v_mfma_f32_16x16x32_bf16 v[40:43], v[160:163], v[176:179], 0
	v_mfma_f32_16x16x32_bf16 v[28:31], v[152:155], v[184:187], 0
	v_mfma_f32_16x16x32_bf16 v[24:27], v[160:163], v[184:187], 0
	v_mfma_f32_16x16x32_bf16 v[12:15], v[152:155], v[192:195], 0
	v_mfma_f32_16x16x32_bf16 v[8:11], v[160:163], v[192:195], 0
	v_mfma_f32_16x16x32_bf16 v[60:63], v[156:159], v[172:175], v[60:63]
	v_mfma_f32_16x16x32_bf16 v[56:59], v[164:167], v[172:175], v[56:59]
	v_mfma_f32_16x16x32_bf16 v[44:47], v[156:159], v[180:183], v[44:47]
	v_mfma_f32_16x16x32_bf16 v[40:43], v[164:167], v[180:183], v[40:43]
	v_mfma_f32_16x16x32_bf16 v[28:31], v[156:159], v[188:191], v[28:31]
	v_mfma_f32_16x16x32_bf16 v[24:27], v[164:167], v[188:191], v[24:27]
	v_mfma_f32_16x16x32_bf16 v[12:15], v[156:159], v[196:199], v[12:15]
	v_mfma_f32_16x16x32_bf16 v[8:11], v[164:167], v[196:199], v[8:11]
	s_barrier
	s_add_u32 s58, s26, 0x40000
	s_addc_u32 s59, s27, 0
	s_add_i32 s60, s48, s31
	s_mov_b32 m0, s60
	s_nop 0
	global_load_lds_dwordx4 v132, s[58:59]
	s_add_i32 m0, s60, 0x2000
	s_nop 0
	global_load_lds_dwordx4 v128, s[58:59]
	s_waitcnt vmcnt(10)
	s_barrier
	v_mfma_f32_16x16x32_bf16 v[52:55], v[200:203], v[168:171], 0
	v_mfma_f32_16x16x32_bf16 v[48:51], v[208:211], v[168:171], 0
	v_mfma_f32_16x16x32_bf16 v[36:39], v[200:203], v[176:179], 0
	v_mfma_f32_16x16x32_bf16 v[32:35], v[208:211], v[176:179], 0
	v_mfma_f32_16x16x32_bf16 v[20:23], v[200:203], v[184:187], 0
	v_mfma_f32_16x16x32_bf16 v[16:19], v[208:211], v[184:187], 0
	v_mfma_f32_16x16x32_bf16 v[4:7], v[200:203], v[192:195], 0
	v_mfma_f32_16x16x32_bf16 v[0:3], v[208:211], v[192:195], 0
	v_mfma_f32_16x16x32_bf16 v[52:55], v[204:207], v[172:175], v[52:55]
	v_mfma_f32_16x16x32_bf16 v[48:51], v[212:215], v[172:175], v[48:51]
	v_mfma_f32_16x16x32_bf16 v[36:39], v[204:207], v[180:183], v[36:39]
	v_mfma_f32_16x16x32_bf16 v[32:35], v[212:215], v[180:183], v[32:35]
	v_mfma_f32_16x16x32_bf16 v[20:23], v[204:207], v[188:191], v[20:23]
	v_mfma_f32_16x16x32_bf16 v[16:19], v[212:215], v[188:191], v[16:19]
	v_mfma_f32_16x16x32_bf16 v[4:7], v[204:207], v[196:199], v[4:7]
	v_mfma_f32_16x16x32_bf16 v[0:3], v[212:215], v[196:199], v[0:3]
	s_add_i32 s58, 0, 0x18000
	v_add_u32_e32 v151, s58, v145
	s_barrier
	s_branch .Lg893_mid
.LBB0_893:
	ds_read_b128 v[152:155], v148
	ds_read_b128 v[156:159], v148 offset:1024
	ds_read_b128 v[160:163], v148 offset:2048
	ds_read_b128 v[164:167], v148 offset:3072
	s_add_u32 s26, s20, 0xfffc0080
	s_addc_u32 s27, s21, -1
	s_cmp_eq_u32 s57, 12
	s_cselect_b32 s29, s13, s27
	s_cselect_b32 s28, s53, s26
	s_cselect_b32 s27, s11, s56
	s_cselect_b32 s26, s54, s55
	s_add_i32 m0, s19, 0xc000
	ds_read_b128 v[168:171], v149
	ds_read_b128 v[172:175], v149 offset:1024
	ds_read_b128 v[176:179], v149 offset:2048
	ds_read_b128 v[180:183], v149 offset:3072
	ds_read_b128 v[184:187], v149 offset:4096
	ds_read_b128 v[188:191], v149 offset:5120
	ds_read_b128 v[192:195], v149 offset:6144
	ds_read_b128 v[196:199], v149 offset:7168
	global_load_lds_dwordx4 v136, s[20:21]
	s_add_i32 m0, s19, 0xe000
	s_nop 0
	global_load_lds_dwordx4 v138, s[20:21]
	s_waitcnt lgkmcnt(8)
	s_waitcnt vmcnt(10)
	s_barrier
	s_waitcnt lgkmcnt(0)
	s_waitcnt lgkmcnt(0)
	v_mfma_f32_16x16x32_bf16 v[124:127], v[152:155], v[168:171], v[124:127]
	v_mfma_f32_16x16x32_bf16 v[120:123], v[160:163], v[168:171], v[120:123]
	v_mfma_f32_16x16x32_bf16 v[108:111], v[152:155], v[176:179], v[108:111]
	v_mfma_f32_16x16x32_bf16 v[104:107], v[160:163], v[176:179], v[104:107]
	v_mfma_f32_16x16x32_bf16 v[92:95], v[152:155], v[184:187], v[92:95]
	v_mfma_f32_16x16x32_bf16 v[88:91], v[160:163], v[184:187], v[88:91]
	v_mfma_f32_16x16x32_bf16 v[76:79], v[152:155], v[192:195], v[76:79]
	v_mfma_f32_16x16x32_bf16 v[72:75], v[160:163], v[192:195], v[72:75]
	v_mfma_f32_16x16x32_bf16 v[124:127], v[156:159], v[172:175], v[124:127]
	v_mfma_f32_16x16x32_bf16 v[120:123], v[164:167], v[172:175], v[120:123]
	v_mfma_f32_16x16x32_bf16 v[108:111], v[156:159], v[180:183], v[108:111]
	v_mfma_f32_16x16x32_bf16 v[104:107], v[164:167], v[180:183], v[104:107]
	v_mfma_f32_16x16x32_bf16 v[92:95], v[156:159], v[188:191], v[92:95]
	v_mfma_f32_16x16x32_bf16 v[88:91], v[164:167], v[188:191], v[88:91]
	v_mfma_f32_16x16x32_bf16 v[76:79], v[156:159], v[196:199], v[76:79]
	v_mfma_f32_16x16x32_bf16 v[72:75], v[164:167], v[196:199], v[72:75]
	s_barrier
	s_add_i32 s58, s47, s31
	s_add_u32 s80, s26, 0x80
	s_addc_u32 s81, s27, 0
	s_mov_b32 m0, s58
	ds_read_b128 v[200:203], v150
	ds_read_b128 v[204:207], v150 offset:1024
	ds_read_b128 v[208:211], v150 offset:2048
	ds_read_b128 v[212:215], v150 offset:3072
	global_load_lds_dwordx4 v132, s[26:27]
	s_add_i32 m0, s58, 0x2000
	s_nop 0
	global_load_lds_dwordx4 v128, s[26:27]
	s_waitcnt vmcnt(10)
	s_barrier
	s_waitcnt lgkmcnt(0)
	s_waitcnt lgkmcnt(0)
	v_mfma_f32_16x16x32_bf16 v[116:119], v[200:203], v[168:171], v[116:119]
	v_mfma_f32_16x16x32_bf16 v[112:115], v[208:211], v[168:171], v[112:115]
	v_mfma_f32_16x16x32_bf16 v[100:103], v[200:203], v[176:179], v[100:103]
	v_mfma_f32_16x16x32_bf16 v[96:99], v[208:211], v[176:179], v[96:99]
	v_mfma_f32_16x16x32_bf16 v[84:87], v[200:203], v[184:187], v[84:87]
	v_mfma_f32_16x16x32_bf16 v[80:83], v[208:211], v[184:187], v[80:83]
	v_mfma_f32_16x16x32_bf16 v[68:71], v[200:203], v[192:195], v[68:71]
	v_mfma_f32_16x16x32_bf16 v[64:67], v[208:211], v[192:195], v[64:67]
	v_mfma_f32_16x16x32_bf16 v[116:119], v[204:207], v[172:175], v[116:119]
	v_mfma_f32_16x16x32_bf16 v[112:115], v[212:215], v[172:175], v[112:115]
	v_mfma_f32_16x16x32_bf16 v[100:103], v[204:207], v[180:183], v[100:103]
	v_mfma_f32_16x16x32_bf16 v[96:99], v[212:215], v[180:183], v[96:99]
	v_mfma_f32_16x16x32_bf16 v[84:87], v[204:207], v[188:191], v[84:87]
	v_mfma_f32_16x16x32_bf16 v[80:83], v[212:215], v[188:191], v[80:83]
	v_mfma_f32_16x16x32_bf16 v[68:71], v[204:207], v[196:199], v[68:71]
	v_mfma_f32_16x16x32_bf16 v[64:67], v[212:215], v[196:199], v[64:67]
	s_mov_b32 m0, s19
	s_add_u32 s82, s28, 0x80
	s_addc_u32 s83, s29, 0
	s_barrier
	ds_read_b128 v[168:171], v149 offset:16384
	ds_read_b128 v[172:175], v149 offset:17408
	ds_read_b128 v[176:179], v149 offset:18432
	ds_read_b128 v[180:183], v149 offset:19456
	ds_read_b128 v[184:187], v149 offset:20480
	ds_read_b128 v[188:191], v149 offset:21504
	ds_read_b128 v[192:195], v149 offset:22528
	ds_read_b128 v[196:199], v149 offset:23552
	global_load_lds_dwordx4 v134, s[28:29]
	s_mov_b32 m0, s42
	s_nop 0
	global_load_lds_dwordx4 v130, s[28:29]
	s_barrier
	s_waitcnt lgkmcnt(0)
	s_waitcnt lgkmcnt(0)
	v_mfma_f32_16x16x32_bf16 v[60:63], v[152:155], v[168:171], v[60:63]
	v_mfma_f32_16x16x32_bf16 v[56:59], v[160:163], v[168:171], v[56:59]
	v_mfma_f32_16x16x32_bf16 v[44:47], v[152:155], v[176:179], v[44:47]
	v_mfma_f32_16x16x32_bf16 v[40:43], v[160:163], v[176:179], v[40:43]
	v_mfma_f32_16x16x32_bf16 v[28:31], v[152:155], v[184:187], v[28:31]
	v_mfma_f32_16x16x32_bf16 v[24:27], v[160:163], v[184:187], v[24:27]
	v_mfma_f32_16x16x32_bf16 v[12:15], v[152:155], v[192:195], v[12:15]
	v_mfma_f32_16x16x32_bf16 v[8:11], v[160:163], v[192:195], v[8:11]
	v_mfma_f32_16x16x32_bf16 v[60:63], v[156:159], v[172:175], v[60:63]
	v_mfma_f32_16x16x32_bf16 v[56:59], v[164:167], v[172:175], v[56:59]
	v_mfma_f32_16x16x32_bf16 v[44:47], v[156:159], v[180:183], v[44:47]
	v_mfma_f32_16x16x32_bf16 v[40:43], v[164:167], v[180:183], v[40:43]
	v_mfma_f32_16x16x32_bf16 v[28:31], v[156:159], v[188:191], v[28:31]
	v_mfma_f32_16x16x32_bf16 v[24:27], v[164:167], v[188:191], v[24:27]
	v_mfma_f32_16x16x32_bf16 v[12:15], v[156:159], v[196:199], v[12:15]
	v_mfma_f32_16x16x32_bf16 v[8:11], v[164:167], v[196:199], v[8:11]
	s_barrier
	s_add_u32 s58, s26, 0x40000
	s_addc_u32 s59, s27, 0
	s_add_i32 s60, s48, s31
	s_mov_b32 m0, s60
	s_nop 0
	global_load_lds_dwordx4 v132, s[58:59]
	s_add_i32 m0, s60, 0x2000
	s_nop 0
	global_load_lds_dwordx4 v128, s[58:59]
	s_waitcnt vmcnt(10)
	s_barrier
	v_mfma_f32_16x16x32_bf16 v[52:55], v[200:203], v[168:171], v[52:55]
	v_mfma_f32_16x16x32_bf16 v[48:51], v[208:211], v[168:171], v[48:51]
	v_mfma_f32_16x16x32_bf16 v[36:39], v[200:203], v[176:179], v[36:39]
	v_mfma_f32_16x16x32_bf16 v[32:35], v[208:211], v[176:179], v[32:35]
	v_mfma_f32_16x16x32_bf16 v[20:23], v[200:203], v[184:187], v[20:23]
	v_mfma_f32_16x16x32_bf16 v[16:19], v[208:211], v[184:187], v[16:19]
	v_mfma_f32_16x16x32_bf16 v[4:7], v[200:203], v[192:195], v[4:7]
	v_mfma_f32_16x16x32_bf16 v[0:3], v[208:211], v[192:195], v[0:3]
	v_mfma_f32_16x16x32_bf16 v[52:55], v[204:207], v[172:175], v[52:55]
	v_mfma_f32_16x16x32_bf16 v[48:51], v[212:215], v[172:175], v[48:51]
	v_mfma_f32_16x16x32_bf16 v[36:39], v[204:207], v[180:183], v[36:39]
	v_mfma_f32_16x16x32_bf16 v[32:35], v[212:215], v[180:183], v[32:35]
	v_mfma_f32_16x16x32_bf16 v[20:23], v[204:207], v[188:191], v[20:23]
	v_mfma_f32_16x16x32_bf16 v[16:19], v[212:215], v[188:191], v[16:19]
	v_mfma_f32_16x16x32_bf16 v[4:7], v[204:207], v[196:199], v[4:7]
	v_mfma_f32_16x16x32_bf16 v[0:3], v[212:215], v[196:199], v[0:3]
	s_add_i32 s58, 0, 0x18000
	v_add_u32_e32 v151, s58, v145
	s_barrier
.Lg893_mid:
	ds_read_b128 v[152:155], v151
	ds_read_b128 v[156:159], v151 offset:1024
	ds_read_b128 v[160:163], v151 offset:2048
	ds_read_b128 v[164:167], v151 offset:3072
	s_add_u32 s28, s28, 0x40000
	s_addc_u32 s29, s29, 0
	s_mov_b32 m0, s43
	ds_read_b128 v[168:171], v149 offset:32768
	ds_read_b128 v[172:175], v149 offset:33792
	ds_read_b128 v[176:179], v149 offset:34816
	ds_read_b128 v[180:183], v149 offset:35840
	ds_read_b128 v[184:187], v149 offset:36864
	ds_read_b128 v[188:191], v149 offset:37888
	ds_read_b128 v[192:195], v149 offset:38912
	ds_read_b128 v[196:199], v149 offset:39936
	global_load_lds_dwordx4 v134, s[28:29]
	s_mov_b32 m0, s44
	s_nop 0
	global_load_lds_dwordx4 v130, s[28:29]
	s_waitcnt lgkmcnt(8)
	s_waitcnt vmcnt(10)
	s_barrier
	s_waitcnt lgkmcnt(0)
	s_waitcnt lgkmcnt(0)
	v_mfma_f32_16x16x32_bf16 v[124:127], v[152:155], v[168:171], v[124:127]
	v_mfma_f32_16x16x32_bf16 v[120:123], v[160:163], v[168:171], v[120:123]
	v_mfma_f32_16x16x32_bf16 v[108:111], v[152:155], v[176:179], v[108:111]
	v_mfma_f32_16x16x32_bf16 v[104:107], v[160:163], v[176:179], v[104:107]
	v_mfma_f32_16x16x32_bf16 v[92:95], v[152:155], v[184:187], v[92:95]
	v_mfma_f32_16x16x32_bf16 v[88:91], v[160:163], v[184:187], v[88:91]
	v_mfma_f32_16x16x32_bf16 v[76:79], v[152:155], v[192:195], v[76:79]
	v_mfma_f32_16x16x32_bf16 v[72:75], v[160:163], v[192:195], v[72:75]
	v_mfma_f32_16x16x32_bf16 v[124:127], v[156:159], v[172:175], v[124:127]
	v_mfma_f32_16x16x32_bf16 v[120:123], v[164:167], v[172:175], v[120:123]
	v_mfma_f32_16x16x32_bf16 v[108:111], v[156:159], v[180:183], v[108:111]
	v_mfma_f32_16x16x32_bf16 v[104:107], v[164:167], v[180:183], v[104:107]
	v_mfma_f32_16x16x32_bf16 v[92:95], v[156:159], v[188:191], v[92:95]
	v_mfma_f32_16x16x32_bf16 v[88:91], v[164:167], v[188:191], v[88:91]
	v_mfma_f32_16x16x32_bf16 v[76:79], v[156:159], v[196:199], v[76:79]
	v_mfma_f32_16x16x32_bf16 v[72:75], v[164:167], v[196:199], v[72:75]
	s_barrier
	s_add_i32 s28, 0, 0x1c000
	s_add_i32 s29, s58, s31
	v_add_u32_e32 v151, s28, v145
	s_mov_b32 m0, s29
	ds_read_b128 v[200:203], v151
	ds_read_b128 v[204:207], v151 offset:1024
	ds_read_b128 v[208:211], v151 offset:2048
	ds_read_b128 v[212:215], v151 offset:3072
	global_load_lds_dwordx4 v132, s[80:81]
	s_add_i32 m0, s29, 0x2000
	s_nop 0
	global_load_lds_dwordx4 v128, s[80:81]
	s_waitcnt vmcnt(10)
	s_barrier
	s_waitcnt lgkmcnt(0)
	s_waitcnt lgkmcnt(0)
	v_mfma_f32_16x16x32_bf16 v[116:119], v[200:203], v[168:171], v[116:119]
	v_mfma_f32_16x16x32_bf16 v[112:115], v[208:211], v[168:171], v[112:115]
	v_mfma_f32_16x16x32_bf16 v[100:103], v[200:203], v[176:179], v[100:103]
	v_mfma_f32_16x16x32_bf16 v[96:99], v[208:211], v[176:179], v[96:99]
	v_mfma_f32_16x16x32_bf16 v[84:87], v[200:203], v[184:187], v[84:87]
	v_mfma_f32_16x16x32_bf16 v[80:83], v[208:211], v[184:187], v[80:83]
	v_mfma_f32_16x16x32_bf16 v[68:71], v[200:203], v[192:195], v[68:71]
	v_mfma_f32_16x16x32_bf16 v[64:67], v[208:211], v[192:195], v[64:67]
	v_mfma_f32_16x16x32_bf16 v[116:119], v[204:207], v[172:175], v[116:119]
	v_mfma_f32_16x16x32_bf16 v[112:115], v[212:215], v[172:175], v[112:115]
	v_mfma_f32_16x16x32_bf16 v[100:103], v[204:207], v[180:183], v[100:103]
	v_mfma_f32_16x16x32_bf16 v[96:99], v[212:215], v[180:183], v[96:99]
	v_mfma_f32_16x16x32_bf16 v[84:87], v[204:207], v[188:191], v[84:87]
	v_mfma_f32_16x16x32_bf16 v[80:83], v[212:215], v[188:191], v[80:83]
	v_mfma_f32_16x16x32_bf16 v[68:71], v[204:207], v[196:199], v[68:71]
	v_mfma_f32_16x16x32_bf16 v[64:67], v[212:215], v[196:199], v[64:67]
	s_mov_b32 m0, s45
	s_barrier
	ds_read_b128 v[168:171], v149 offset:49152
	ds_read_b128 v[172:175], v149 offset:50176
	ds_read_b128 v[176:179], v149 offset:51200
	ds_read_b128 v[180:183], v149 offset:52224
	ds_read_b128 v[184:187], v149 offset:53248
	ds_read_b128 v[188:191], v149 offset:54272
	ds_read_b128 v[192:195], v149 offset:55296
	ds_read_b128 v[196:199], v149 offset:56320
	global_load_lds_dwordx4 v134, s[82:83]
	s_mov_b32 m0, s46
	s_nop 0
	global_load_lds_dwordx4 v130, s[82:83]
	s_barrier
	s_waitcnt lgkmcnt(0)
	s_waitcnt lgkmcnt(0)
	v_mfma_f32_16x16x32_bf16 v[60:63], v[152:155], v[168:171], v[60:63]
	v_mfma_f32_16x16x32_bf16 v[56:59], v[160:163], v[168:171], v[56:59]
	v_mfma_f32_16x16x32_bf16 v[44:47], v[152:155], v[176:179], v[44:47]
	v_mfma_f32_16x16x32_bf16 v[40:43], v[160:163], v[176:179], v[40:43]
	v_mfma_f32_16x16x32_bf16 v[28:31], v[152:155], v[184:187], v[28:31]
	v_mfma_f32_16x16x32_bf16 v[24:27], v[160:163], v[184:187], v[24:27]
	v_mfma_f32_16x16x32_bf16 v[12:15], v[152:155], v[192:195], v[12:15]
	v_mfma_f32_16x16x32_bf16 v[8:11], v[160:163], v[192:195], v[8:11]
	v_mfma_f32_16x16x32_bf16 v[60:63], v[156:159], v[172:175], v[60:63]
	v_mfma_f32_16x16x32_bf16 v[56:59], v[164:167], v[172:175], v[56:59]
	v_mfma_f32_16x16x32_bf16 v[44:47], v[156:159], v[180:183], v[44:47]
	v_mfma_f32_16x16x32_bf16 v[40:43], v[164:167], v[180:183], v[40:43]
	v_mfma_f32_16x16x32_bf16 v[28:31], v[156:159], v[188:191], v[28:31]
	v_mfma_f32_16x16x32_bf16 v[24:27], v[164:167], v[188:191], v[24:27]
	v_mfma_f32_16x16x32_bf16 v[12:15], v[156:159], v[196:199], v[12:15]
	v_mfma_f32_16x16x32_bf16 v[8:11], v[164:167], v[196:199], v[8:11]
	s_barrier
	s_add_u32 s26, s26, 0x40080
	s_addc_u32 s27, s27, 0
	s_add_i32 s28, s28, s31
	s_mov_b32 m0, s28
	s_nop 0
	global_load_lds_dwordx4 v132, s[26:27]
	s_add_i32 m0, s28, 0x2000
	s_nop 0
	global_load_lds_dwordx4 v128, s[26:27]
	s_waitcnt vmcnt(10)
	s_barrier
	v_mfma_f32_16x16x32_bf16 v[52:55], v[200:203], v[168:171], v[52:55]
	v_mfma_f32_16x16x32_bf16 v[48:51], v[208:211], v[168:171], v[48:51]
	v_mfma_f32_16x16x32_bf16 v[36:39], v[200:203], v[176:179], v[36:39]
	v_mfma_f32_16x16x32_bf16 v[32:35], v[208:211], v[176:179], v[32:35]
	v_mfma_f32_16x16x32_bf16 v[20:23], v[200:203], v[184:187], v[20:23]
	v_mfma_f32_16x16x32_bf16 v[16:19], v[208:211], v[184:187], v[16:19]
	v_mfma_f32_16x16x32_bf16 v[4:7], v[200:203], v[192:195], v[4:7]
	v_mfma_f32_16x16x32_bf16 v[0:3], v[208:211], v[192:195], v[0:3]
	v_mfma_f32_16x16x32_bf16 v[52:55], v[204:207], v[172:175], v[52:55]
	v_mfma_f32_16x16x32_bf16 v[48:51], v[212:215], v[172:175], v[48:51]
	v_mfma_f32_16x16x32_bf16 v[36:39], v[204:207], v[180:183], v[36:39]
	v_mfma_f32_16x16x32_bf16 v[32:35], v[212:215], v[180:183], v[32:35]
	v_mfma_f32_16x16x32_bf16 v[20:23], v[204:207], v[188:191], v[20:23]
	v_mfma_f32_16x16x32_bf16 v[16:19], v[212:215], v[188:191], v[16:19]
	v_mfma_f32_16x16x32_bf16 v[4:7], v[204:207], v[196:199], v[4:7]
	v_mfma_f32_16x16x32_bf16 v[0:3], v[212:215], v[196:199], v[0:3]
	s_add_i32 s57, s57, 2
	s_add_u32 s20, s20, 0x100
	s_addc_u32 s21, s21, 0
	s_add_u32 s55, s55, 0x100
	s_addc_u32 s56, s56, 0
	s_cmp_gt_u32 s57, 13
	s_barrier
	s_cbranch_scc0 .LBB0_893
	s_setprio 0
	s_cmpk_gt_u32 s30, 0xff
	s_cbranch_scc1 .Lg893_nox
	s_barrier
	s_setprio 1

.Lg973_noy:
	ds_read_b128 v[146:149], v203
	ds_read_b128 v[150:153], v203 offset:1024
	ds_read_b128 v[154:157], v203 offset:2048
	ds_read_b128 v[158:161], v203 offset:3072
	s_add_u32 s22, s20, 0x100
	s_addc_u32 s23, s21, 0
	s_cmp_eq_u32 s56, 40
	s_cselect_b32 s27, s5, s23
	s_cselect_b32 s26, s4, s22
	s_cselect_b32 s25, s7, s55
	s_cselect_b32 s24, s6, s54
	s_add_i32 m0, s37, 0xc000
	ds_read_b128 v[162:165], v204
	ds_read_b128 v[166:169], v204 offset:1024
	ds_read_b128 v[170:173], v204 offset:2048
	ds_read_b128 v[174:177], v204 offset:3072
	ds_read_b128 v[178:181], v204 offset:4096
	ds_read_b128 v[182:185], v204 offset:5120
	ds_read_b128 v[186:189], v204 offset:6144
	ds_read_b128 v[190:193], v204 offset:7168
	global_load_lds_dwordx4 v138, s[20:21]
	s_add_i32 m0, s37, 0xe000
	s_nop 0
	global_load_lds_dwordx4 v140, s[20:21]
	s_waitcnt lgkmcnt(8)
	s_waitcnt vmcnt(10)
	s_barrier
	s_waitcnt lgkmcnt(0)
	s_waitcnt lgkmcnt(0)
	v_mfma_f32_16x16x32_bf16 v[124:127], v[146:149], v[162:165], 0
	v_mfma_f32_16x16x32_bf16 v[120:123], v[154:157], v[162:165], 0
	v_mfma_f32_16x16x32_bf16 v[108:111], v[146:149], v[170:173], 0
	v_mfma_f32_16x16x32_bf16 v[104:107], v[154:157], v[170:173], 0
	v_mfma_f32_16x16x32_bf16 v[92:95], v[146:149], v[178:181], 0
	v_mfma_f32_16x16x32_bf16 v[88:91], v[154:157], v[178:181], 0
	v_mfma_f32_16x16x32_bf16 v[76:79], v[146:149], v[186:189], 0
	v_mfma_f32_16x16x32_bf16 v[72:75], v[154:157], v[186:189], 0
	v_mfma_f32_16x16x32_bf16 v[124:127], v[150:153], v[166:169], v[124:127]
	v_mfma_f32_16x16x32_bf16 v[120:123], v[158:161], v[166:169], v[120:123]
	v_mfma_f32_16x16x32_bf16 v[108:111], v[150:153], v[174:177], v[108:111]
	v_mfma_f32_16x16x32_bf16 v[104:107], v[158:161], v[174:177], v[104:107]
	v_mfma_f32_16x16x32_bf16 v[92:95], v[150:153], v[182:185], v[92:95]
	v_mfma_f32_16x16x32_bf16 v[88:91], v[158:161], v[182:185], v[88:91]
	v_mfma_f32_16x16x32_bf16 v[76:79], v[150:153], v[190:193], v[76:79]
	v_mfma_f32_16x16x32_bf16 v[72:75], v[158:161], v[190:193], v[72:75]
	s_barrier
	s_add_i32 s20, s47, s36
	s_add_u32 s80, s24, 0x80
	s_addc_u32 s81, s25, 0
	s_mov_b32 m0, s20
	ds_read_b128 v[194:197], v205
	ds_read_b128 v[208:211], v205 offset:1024
	ds_read_b128 v[212:215], v205 offset:2048
	ds_read_b128 v[216:219], v205 offset:3072
	global_load_lds_dwordx4 v130, s[24:25]
	s_add_i32 m0, s20, 0x2000
	s_nop 0
	global_load_lds_dwordx4 v134, s[24:25]
	s_waitcnt vmcnt(10)
	s_barrier
	s_waitcnt lgkmcnt(0)
	s_waitcnt lgkmcnt(0)
	v_mfma_f32_16x16x32_bf16 v[116:119], v[194:197], v[162:165], 0
	v_mfma_f32_16x16x32_bf16 v[112:115], v[212:215], v[162:165], 0
	v_mfma_f32_16x16x32_bf16 v[100:103], v[194:197], v[170:173], 0
	v_mfma_f32_16x16x32_bf16 v[96:99], v[212:215], v[170:173], 0
	v_mfma_f32_16x16x32_bf16 v[84:87], v[194:197], v[178:181], 0
	v_mfma_f32_16x16x32_bf16 v[80:83], v[212:215], v[178:181], 0
	v_mfma_f32_16x16x32_bf16 v[68:71], v[194:197], v[186:189], 0
	v_mfma_f32_16x16x32_bf16 v[64:67], v[212:215], v[186:189], 0
	v_mfma_f32_16x16x32_bf16 v[116:119], v[208:211], v[166:169], v[116:119]
	v_mfma_f32_16x16x32_bf16 v[112:115], v[216:219], v[166:169], v[112:115]
	v_mfma_f32_16x16x32_bf16 v[100:103], v[208:211], v[174:177], v[100:103]
	v_mfma_f32_16x16x32_bf16 v[96:99], v[216:219], v[174:177], v[96:99]
	v_mfma_f32_16x16x32_bf16 v[84:87], v[208:211], v[182:185], v[84:87]
	v_mfma_f32_16x16x32_bf16 v[80:83], v[216:219], v[182:185], v[80:83]
	v_mfma_f32_16x16x32_bf16 v[68:71], v[208:211], v[190:193], v[68:71]
	v_mfma_f32_16x16x32_bf16 v[64:67], v[216:219], v[190:193], v[64:67]
	s_mov_b32 m0, s37
	s_add_u32 s82, s26, 0x80
	s_addc_u32 s83, s27, 0
	s_barrier
	ds_read_b128 v[162:165], v204 offset:16384
	ds_read_b128 v[166:169], v204 offset:17408
	ds_read_b128 v[170:173], v204 offset:18432
	ds_read_b128 v[174:177], v204 offset:19456
	ds_read_b128 v[178:181], v204 offset:20480
	ds_read_b128 v[182:185], v204 offset:21504
	ds_read_b128 v[186:189], v204 offset:22528
	ds_read_b128 v[190:193], v204 offset:23552
	global_load_lds_dwordx4 v128, s[26:27]
	s_mov_b32 m0, s38
	s_nop 0
	global_load_lds_dwordx4 v132, s[26:27]
	s_barrier
	s_waitcnt lgkmcnt(0)
	s_waitcnt lgkmcnt(0)
	v_mfma_f32_16x16x32_bf16 v[60:63], v[146:149], v[162:165], 0
	v_mfma_f32_16x16x32_bf16 v[56:59], v[154:157], v[162:165], 0
	v_mfma_f32_16x16x32_bf16 v[44:47], v[146:149], v[170:173], 0
	v_mfma_f32_16x16x32_bf16 v[40:43], v[154:157], v[170:173], 0
	v_mfma_f32_16x16x32_bf16 v[28:31], v[146:149], v[178:181], 0
	v_mfma_f32_16x16x32_bf16 v[24:27], v[154:157], v[178:181], 0
	v_mfma_f32_16x16x32_bf16 v[12:15], v[146:149], v[186:189], 0
	v_mfma_f32_16x16x32_bf16 v[8:11], v[154:157], v[186:189], 0
	v_mfma_f32_16x16x32_bf16 v[60:63], v[150:153], v[166:169], v[60:63]
	v_mfma_f32_16x16x32_bf16 v[56:59], v[158:161], v[166:169], v[56:59]
	v_mfma_f32_16x16x32_bf16 v[44:47], v[150:153], v[174:177], v[44:47]
	v_mfma_f32_16x16x32_bf16 v[40:43], v[158:161], v[174:177], v[40:43]
	v_mfma_f32_16x16x32_bf16 v[28:31], v[150:153], v[182:185], v[28:31]
	v_mfma_f32_16x16x32_bf16 v[24:27], v[158:161], v[182:185], v[24:27]
	v_mfma_f32_16x16x32_bf16 v[12:15], v[150:153], v[190:193], v[12:15]
	v_mfma_f32_16x16x32_bf16 v[8:11], v[158:161], v[190:193], v[8:11]
	s_barrier
	s_add_u32 s20, s24, 0xb0000
	s_addc_u32 s21, s25, 0
	s_add_i32 s57, s48, s36
	s_mov_b32 m0, s57
	s_nop 0
	global_load_lds_dwordx4 v130, s[20:21]
	s_add_i32 m0, s57, 0x2000
	s_nop 0
	global_load_lds_dwordx4 v134, s[20:21]
	s_waitcnt vmcnt(10)
	s_barrier
	v_mfma_f32_16x16x32_bf16 v[52:55], v[194:197], v[162:165], 0
	v_mfma_f32_16x16x32_bf16 v[48:51], v[212:215], v[162:165], 0
	v_mfma_f32_16x16x32_bf16 v[36:39], v[194:197], v[170:173], 0
	v_mfma_f32_16x16x32_bf16 v[32:35], v[212:215], v[170:173], 0
	v_mfma_f32_16x16x32_bf16 v[20:23], v[194:197], v[178:181], 0
	v_mfma_f32_16x16x32_bf16 v[16:19], v[212:215], v[178:181], 0
	v_mfma_f32_16x16x32_bf16 v[4:7], v[194:197], v[186:189], 0
	v_mfma_f32_16x16x32_bf16 v[0:3], v[212:215], v[186:189], 0
	v_mfma_f32_16x16x32_bf16 v[52:55], v[208:211], v[166:169], v[52:55]
	v_mfma_f32_16x16x32_bf16 v[48:51], v[216:219], v[166:169], v[48:51]
	v_mfma_f32_16x16x32_bf16 v[36:39], v[208:211], v[174:177], v[36:39]
	v_mfma_f32_16x16x32_bf16 v[32:35], v[216:219], v[174:177], v[32:35]
	v_mfma_f32_16x16x32_bf16 v[20:23], v[208:211], v[182:185], v[20:23]
	v_mfma_f32_16x16x32_bf16 v[16:19], v[216:219], v[182:185], v[16:19]
	v_mfma_f32_16x16x32_bf16 v[4:7], v[208:211], v[190:193], v[4:7]
	v_mfma_f32_16x16x32_bf16 v[0:3], v[216:219], v[190:193], v[0:3]
	s_add_i32 s57, 0, 0x18000
	v_add_u32_e32 v158, s57, v201
	s_barrier
	s_branch .Lg973_mid
.LBB0_973:
	ds_read_b128 v[146:149], v203
	ds_read_b128 v[150:153], v203 offset:1024
	ds_read_b128 v[154:157], v203 offset:2048
	ds_read_b128 v[158:161], v203 offset:3072
	s_add_u32 s22, s20, 0x100
	s_addc_u32 s23, s21, 0
	s_cmp_eq_u32 s56, 40
	s_cselect_b32 s27, s5, s23
	s_cselect_b32 s26, s4, s22
	s_cselect_b32 s25, s7, s55
	s_cselect_b32 s24, s6, s54
	s_add_i32 m0, s37, 0xc000
	ds_read_b128 v[162:165], v204
	ds_read_b128 v[166:169], v204 offset:1024
	ds_read_b128 v[170:173], v204 offset:2048
	ds_read_b128 v[174:177], v204 offset:3072
	ds_read_b128 v[178:181], v204 offset:4096
	ds_read_b128 v[182:185], v204 offset:5120
	ds_read_b128 v[186:189], v204 offset:6144
	ds_read_b128 v[190:193], v204 offset:7168
	global_load_lds_dwordx4 v138, s[20:21]
	s_add_i32 m0, s37, 0xe000
	s_nop 0
	global_load_lds_dwordx4 v140, s[20:21]
	s_waitcnt lgkmcnt(8)
	s_waitcnt vmcnt(10)
	s_barrier
	s_waitcnt lgkmcnt(0)
	s_waitcnt lgkmcnt(0)
	v_mfma_f32_16x16x32_bf16 v[124:127], v[146:149], v[162:165], v[124:127]
	v_mfma_f32_16x16x32_bf16 v[120:123], v[154:157], v[162:165], v[120:123]
	v_mfma_f32_16x16x32_bf16 v[108:111], v[146:149], v[170:173], v[108:111]
	v_mfma_f32_16x16x32_bf16 v[104:107], v[154:157], v[170:173], v[104:107]
	v_mfma_f32_16x16x32_bf16 v[92:95], v[146:149], v[178:181], v[92:95]
	v_mfma_f32_16x16x32_bf16 v[88:91], v[154:157], v[178:181], v[88:91]
	v_mfma_f32_16x16x32_bf16 v[76:79], v[146:149], v[186:189], v[76:79]
	v_mfma_f32_16x16x32_bf16 v[72:75], v[154:157], v[186:189], v[72:75]
	v_mfma_f32_16x16x32_bf16 v[124:127], v[150:153], v[166:169], v[124:127]
	v_mfma_f32_16x16x32_bf16 v[120:123], v[158:161], v[166:169], v[120:123]
	v_mfma_f32_16x16x32_bf16 v[108:111], v[150:153], v[174:177], v[108:111]
	v_mfma_f32_16x16x32_bf16 v[104:107], v[158:161], v[174:177], v[104:107]
	v_mfma_f32_16x16x32_bf16 v[92:95], v[150:153], v[182:185], v[92:95]
	v_mfma_f32_16x16x32_bf16 v[88:91], v[158:161], v[182:185], v[88:91]
	v_mfma_f32_16x16x32_bf16 v[76:79], v[150:153], v[190:193], v[76:79]
	v_mfma_f32_16x16x32_bf16 v[72:75], v[158:161], v[190:193], v[72:75]
	s_barrier
	s_add_i32 s20, s47, s36
	s_add_u32 s80, s24, 0x80
	s_addc_u32 s81, s25, 0
	s_mov_b32 m0, s20
	ds_read_b128 v[194:197], v205
	ds_read_b128 v[208:211], v205 offset:1024
	ds_read_b128 v[212:215], v205 offset:2048
	ds_read_b128 v[216:219], v205 offset:3072
	global_load_lds_dwordx4 v130, s[24:25]
	s_add_i32 m0, s20, 0x2000
	s_nop 0
	global_load_lds_dwordx4 v134, s[24:25]
	s_waitcnt vmcnt(10)
	s_barrier
	s_waitcnt lgkmcnt(0)
	s_waitcnt lgkmcnt(0)
	v_mfma_f32_16x16x32_bf16 v[116:119], v[194:197], v[162:165], v[116:119]
	v_mfma_f32_16x16x32_bf16 v[112:115], v[212:215], v[162:165], v[112:115]
	v_mfma_f32_16x16x32_bf16 v[100:103], v[194:197], v[170:173], v[100:103]
	v_mfma_f32_16x16x32_bf16 v[96:99], v[212:215], v[170:173], v[96:99]
	v_mfma_f32_16x16x32_bf16 v[84:87], v[194:197], v[178:181], v[84:87]
	v_mfma_f32_16x16x32_bf16 v[80:83], v[212:215], v[178:181], v[80:83]
	v_mfma_f32_16x16x32_bf16 v[68:71], v[194:197], v[186:189], v[68:71]
	v_mfma_f32_16x16x32_bf16 v[64:67], v[212:215], v[186:189], v[64:67]
	v_mfma_f32_16x16x32_bf16 v[116:119], v[208:211], v[166:169], v[116:119]
	v_mfma_f32_16x16x32_bf16 v[112:115], v[216:219], v[166:169], v[112:115]
	v_mfma_f32_16x16x32_bf16 v[100:103], v[208:211], v[174:177], v[100:103]
	v_mfma_f32_16x16x32_bf16 v[96:99], v[216:219], v[174:177], v[96:99]
	v_mfma_f32_16x16x32_bf16 v[84:87], v[208:211], v[182:185], v[84:87]
	v_mfma_f32_16x16x32_bf16 v[80:83], v[216:219], v[182:185], v[80:83]
	v_mfma_f32_16x16x32_bf16 v[68:71], v[208:211], v[190:193], v[68:71]
	v_mfma_f32_16x16x32_bf16 v[64:67], v[216:219], v[190:193], v[64:67]
	s_mov_b32 m0, s37
	s_add_u32 s82, s26, 0x80
	s_addc_u32 s83, s27, 0
	s_barrier
	ds_read_b128 v[162:165], v204 offset:16384
	ds_read_b128 v[166:169], v204 offset:17408
	ds_read_b128 v[170:173], v204 offset:18432
	ds_read_b128 v[174:177], v204 offset:19456
	ds_read_b128 v[178:181], v204 offset:20480
	ds_read_b128 v[182:185], v204 offset:21504
	ds_read_b128 v[186:189], v204 offset:22528
	ds_read_b128 v[190:193], v204 offset:23552
	global_load_lds_dwordx4 v128, s[26:27]
	s_mov_b32 m0, s38
	s_nop 0
	global_load_lds_dwordx4 v132, s[26:27]
	s_barrier
	s_waitcnt lgkmcnt(0)
	s_waitcnt lgkmcnt(0)
	v_mfma_f32_16x16x32_bf16 v[60:63], v[146:149], v[162:165], v[60:63]
	v_mfma_f32_16x16x32_bf16 v[56:59], v[154:157], v[162:165], v[56:59]
	v_mfma_f32_16x16x32_bf16 v[44:47], v[146:149], v[170:173], v[44:47]
	v_mfma_f32_16x16x32_bf16 v[40:43], v[154:157], v[170:173], v[40:43]
	v_mfma_f32_16x16x32_bf16 v[28:31], v[146:149], v[178:181], v[28:31]
	v_mfma_f32_16x16x32_bf16 v[24:27], v[154:157], v[178:181], v[24:27]
	v_mfma_f32_16x16x32_bf16 v[12:15], v[146:149], v[186:189], v[12:15]
	v_mfma_f32_16x16x32_bf16 v[8:11], v[154:157], v[186:189], v[8:11]
	v_mfma_f32_16x16x32_bf16 v[60:63], v[150:153], v[166:169], v[60:63]
	v_mfma_f32_16x16x32_bf16 v[56:59], v[158:161], v[166:169], v[56:59]
	v_mfma_f32_16x16x32_bf16 v[44:47], v[150:153], v[174:177], v[44:47]
	v_mfma_f32_16x16x32_bf16 v[40:43], v[158:161], v[174:177], v[40:43]
	v_mfma_f32_16x16x32_bf16 v[28:31], v[150:153], v[182:185], v[28:31]
	v_mfma_f32_16x16x32_bf16 v[24:27], v[158:161], v[182:185], v[24:27]
	v_mfma_f32_16x16x32_bf16 v[12:15], v[150:153], v[190:193], v[12:15]
	v_mfma_f32_16x16x32_bf16 v[8:11], v[158:161], v[190:193], v[8:11]
	s_barrier
	s_add_u32 s20, s24, 0xb0000
	s_addc_u32 s21, s25, 0
	s_add_i32 s57, s48, s36
	s_mov_b32 m0, s57
	s_nop 0
	global_load_lds_dwordx4 v130, s[20:21]
	s_add_i32 m0, s57, 0x2000
	s_nop 0
	global_load_lds_dwordx4 v134, s[20:21]
	s_waitcnt vmcnt(10)
	s_barrier
	v_mfma_f32_16x16x32_bf16 v[52:55], v[194:197], v[162:165], v[52:55]
	v_mfma_f32_16x16x32_bf16 v[48:51], v[212:215], v[162:165], v[48:51]
	v_mfma_f32_16x16x32_bf16 v[36:39], v[194:197], v[170:173], v[36:39]
	v_mfma_f32_16x16x32_bf16 v[32:35], v[212:215], v[170:173], v[32:35]
	v_mfma_f32_16x16x32_bf16 v[20:23], v[194:197], v[178:181], v[20:23]
	v_mfma_f32_16x16x32_bf16 v[16:19], v[212:215], v[178:181], v[16:19]
	v_mfma_f32_16x16x32_bf16 v[4:7], v[194:197], v[186:189], v[4:7]
	v_mfma_f32_16x16x32_bf16 v[0:3], v[212:215], v[186:189], v[0:3]
	v_mfma_f32_16x16x32_bf16 v[52:55], v[208:211], v[166:169], v[52:55]
	v_mfma_f32_16x16x32_bf16 v[48:51], v[216:219], v[166:169], v[48:51]
	v_mfma_f32_16x16x32_bf16 v[36:39], v[208:211], v[174:177], v[36:39]
	v_mfma_f32_16x16x32_bf16 v[32:35], v[216:219], v[174:177], v[32:35]
	v_mfma_f32_16x16x32_bf16 v[20:23], v[208:211], v[182:185], v[20:23]
	v_mfma_f32_16x16x32_bf16 v[16:19], v[216:219], v[182:185], v[16:19]
	v_mfma_f32_16x16x32_bf16 v[4:7], v[208:211], v[190:193], v[4:7]
	v_mfma_f32_16x16x32_bf16 v[0:3], v[216:219], v[190:193], v[0:3]
	s_add_i32 s57, 0, 0x18000
	v_add_u32_e32 v158, s57, v201
	s_barrier
.Lg973_mid:
	ds_read_b128 v[146:149], v158
	ds_read_b128 v[150:153], v158 offset:1024
	ds_read_b128 v[154:157], v158 offset:2048
	ds_read_b128 v[158:161], v158 offset:3072
	s_add_u32 s20, s26, 0xb0000
	s_addc_u32 s21, s27, 0
	s_mov_b32 m0, s39
	ds_read_b128 v[162:165], v204 offset:32768
	ds_read_b128 v[166:169], v204 offset:33792
	ds_read_b128 v[170:173], v204 offset:34816
	ds_read_b128 v[174:177], v204 offset:35840
	ds_read_b128 v[178:181], v204 offset:36864
	ds_read_b128 v[182:185], v204 offset:37888
	ds_read_b128 v[186:189], v204 offset:38912
	ds_read_b128 v[190:193], v204 offset:39936
	global_load_lds_dwordx4 v128, s[20:21]
	s_mov_b32 m0, s40
	s_nop 0
	global_load_lds_dwordx4 v132, s[20:21]
	s_waitcnt lgkmcnt(8)
	s_waitcnt vmcnt(10)
	s_barrier
	s_waitcnt lgkmcnt(0)
	s_waitcnt lgkmcnt(0)
	v_mfma_f32_16x16x32_bf16 v[124:127], v[146:149], v[162:165], v[124:127]
	v_mfma_f32_16x16x32_bf16 v[120:123], v[154:157], v[162:165], v[120:123]
	v_mfma_f32_16x16x32_bf16 v[108:111], v[146:149], v[170:173], v[108:111]
	v_mfma_f32_16x16x32_bf16 v[104:107], v[154:157], v[170:173], v[104:107]
	v_mfma_f32_16x16x32_bf16 v[92:95], v[146:149], v[178:181], v[92:95]
	v_mfma_f32_16x16x32_bf16 v[88:91], v[154:157], v[178:181], v[88:91]
	v_mfma_f32_16x16x32_bf16 v[76:79], v[146:149], v[186:189], v[76:79]
	v_mfma_f32_16x16x32_bf16 v[72:75], v[154:157], v[186:189], v[72:75]
	v_mfma_f32_16x16x32_bf16 v[124:127], v[150:153], v[166:169], v[124:127]
	v_mfma_f32_16x16x32_bf16 v[120:123], v[158:161], v[166:169], v[120:123]
	v_mfma_f32_16x16x32_bf16 v[108:111], v[150:153], v[174:177], v[108:111]
	v_mfma_f32_16x16x32_bf16 v[104:107], v[158:161], v[174:177], v[104:107]
	v_mfma_f32_16x16x32_bf16 v[92:95], v[150:153], v[182:185], v[92:95]
	v_mfma_f32_16x16x32_bf16 v[88:91], v[158:161], v[182:185], v[88:91]
	v_mfma_f32_16x16x32_bf16 v[76:79], v[150:153], v[190:193], v[76:79]
	v_mfma_f32_16x16x32_bf16 v[72:75], v[158:161], v[190:193], v[72:75]
	s_barrier
	s_add_i32 s26, 0, 0x1c000
	s_add_i32 s20, s57, s36
	v_add_u32_e32 v216, s26, v201
	s_mov_b32 m0, s20
	ds_read_b128 v[194:197], v216
	ds_read_b128 v[208:211], v216 offset:1024
	ds_read_b128 v[212:215], v216 offset:2048
	ds_read_b128 v[216:219], v216 offset:3072
	global_load_lds_dwordx4 v130, s[80:81]
	s_add_i32 m0, s20, 0x2000
	s_nop 0
	global_load_lds_dwordx4 v134, s[80:81]
	s_waitcnt vmcnt(10)
	s_barrier
	s_waitcnt lgkmcnt(0)
	s_waitcnt lgkmcnt(0)
	v_mfma_f32_16x16x32_bf16 v[116:119], v[194:197], v[162:165], v[116:119]
	v_mfma_f32_16x16x32_bf16 v[112:115], v[212:215], v[162:165], v[112:115]
	v_mfma_f32_16x16x32_bf16 v[100:103], v[194:197], v[170:173], v[100:103]
	v_mfma_f32_16x16x32_bf16 v[96:99], v[212:215], v[170:173], v[96:99]
	v_mfma_f32_16x16x32_bf16 v[84:87], v[194:197], v[178:181], v[84:87]
	v_mfma_f32_16x16x32_bf16 v[80:83], v[212:215], v[178:181], v[80:83]
	v_mfma_f32_16x16x32_bf16 v[68:71], v[194:197], v[186:189], v[68:71]
	v_mfma_f32_16x16x32_bf16 v[64:67], v[212:215], v[186:189], v[64:67]
	v_mfma_f32_16x16x32_bf16 v[116:119], v[208:211], v[166:169], v[116:119]
	v_mfma_f32_16x16x32_bf16 v[112:115], v[216:219], v[166:169], v[112:115]
	v_mfma_f32_16x16x32_bf16 v[100:103], v[208:211], v[174:177], v[100:103]
	v_mfma_f32_16x16x32_bf16 v[96:99], v[216:219], v[174:177], v[96:99]
	v_mfma_f32_16x16x32_bf16 v[84:87], v[208:211], v[182:185], v[84:87]
	v_mfma_f32_16x16x32_bf16 v[80:83], v[216:219], v[182:185], v[80:83]
	v_mfma_f32_16x16x32_bf16 v[68:71], v[208:211], v[190:193], v[68:71]
	v_mfma_f32_16x16x32_bf16 v[64:67], v[216:219], v[190:193], v[64:67]
	s_mov_b32 m0, s42
	s_barrier
	ds_read_b128 v[162:165], v204 offset:49152
	ds_read_b128 v[166:169], v204 offset:50176
	ds_read_b128 v[170:173], v204 offset:51200
	ds_read_b128 v[174:177], v204 offset:52224
	ds_read_b128 v[178:181], v204 offset:53248
	ds_read_b128 v[182:185], v204 offset:54272
	ds_read_b128 v[186:189], v204 offset:55296
	ds_read_b128 v[190:193], v204 offset:56320
	global_load_lds_dwordx4 v128, s[82:83]
	s_mov_b32 m0, s43
	s_nop 0
	global_load_lds_dwordx4 v132, s[82:83]
	s_barrier
	s_waitcnt lgkmcnt(0)
	s_waitcnt lgkmcnt(0)
	v_mfma_f32_16x16x32_bf16 v[60:63], v[146:149], v[162:165], v[60:63]
	v_mfma_f32_16x16x32_bf16 v[56:59], v[154:157], v[162:165], v[56:59]
	v_mfma_f32_16x16x32_bf16 v[44:47], v[146:149], v[170:173], v[44:47]
	v_mfma_f32_16x16x32_bf16 v[40:43], v[154:157], v[170:173], v[40:43]
	v_mfma_f32_16x16x32_bf16 v[28:31], v[146:149], v[178:181], v[28:31]
	v_mfma_f32_16x16x32_bf16 v[24:27], v[154:157], v[178:181], v[24:27]
	v_mfma_f32_16x16x32_bf16 v[12:15], v[146:149], v[186:189], v[12:15]
	v_mfma_f32_16x16x32_bf16 v[8:11], v[154:157], v[186:189], v[8:11]
	v_mfma_f32_16x16x32_bf16 v[60:63], v[150:153], v[166:169], v[60:63]
	v_mfma_f32_16x16x32_bf16 v[56:59], v[158:161], v[166:169], v[56:59]
	v_mfma_f32_16x16x32_bf16 v[44:47], v[150:153], v[174:177], v[44:47]
	v_mfma_f32_16x16x32_bf16 v[40:43], v[158:161], v[174:177], v[40:43]
	v_mfma_f32_16x16x32_bf16 v[28:31], v[150:153], v[182:185], v[28:31]
	v_mfma_f32_16x16x32_bf16 v[24:27], v[158:161], v[182:185], v[24:27]
	v_mfma_f32_16x16x32_bf16 v[12:15], v[150:153], v[190:193], v[12:15]
	v_mfma_f32_16x16x32_bf16 v[8:11], v[158:161], v[190:193], v[8:11]
	s_barrier
	s_add_u32 s20, s24, 0xb0080
	s_addc_u32 s21, s25, 0
	s_add_i32 s24, s26, s36
	s_mov_b32 m0, s24
	s_nop 0
	global_load_lds_dwordx4 v130, s[20:21]
	s_add_i32 m0, s24, 0x2000
	s_nop 0
	global_load_lds_dwordx4 v134, s[20:21]
	s_waitcnt vmcnt(10)
	s_barrier
	v_mfma_f32_16x16x32_bf16 v[52:55], v[194:197], v[162:165], v[52:55]
	v_mfma_f32_16x16x32_bf16 v[48:51], v[212:215], v[162:165], v[48:51]
	v_mfma_f32_16x16x32_bf16 v[36:39], v[194:197], v[170:173], v[36:39]
	v_mfma_f32_16x16x32_bf16 v[32:35], v[212:215], v[170:173], v[32:35]
	v_mfma_f32_16x16x32_bf16 v[20:23], v[194:197], v[178:181], v[20:23]
	v_mfma_f32_16x16x32_bf16 v[16:19], v[212:215], v[178:181], v[16:19]
	v_mfma_f32_16x16x32_bf16 v[4:7], v[194:197], v[186:189], v[4:7]
	v_mfma_f32_16x16x32_bf16 v[0:3], v[212:215], v[186:189], v[0:3]
	v_mfma_f32_16x16x32_bf16 v[52:55], v[208:211], v[166:169], v[52:55]
	v_mfma_f32_16x16x32_bf16 v[48:51], v[216:219], v[166:169], v[48:51]
	v_mfma_f32_16x16x32_bf16 v[36:39], v[208:211], v[174:177], v[36:39]
	v_mfma_f32_16x16x32_bf16 v[32:35], v[216:219], v[174:177], v[32:35]
	v_mfma_f32_16x16x32_bf16 v[20:23], v[208:211], v[182:185], v[20:23]
	v_mfma_f32_16x16x32_bf16 v[16:19], v[216:219], v[182:185], v[16:19]
	v_mfma_f32_16x16x32_bf16 v[4:7], v[208:211], v[190:193], v[4:7]
	v_mfma_f32_16x16x32_bf16 v[0:3], v[216:219], v[190:193], v[0:3]
	s_add_i32 s56, s56, 2
	s_add_u32 s54, s54, 0x100
	s_addc_u32 s55, s55, 0
	s_cmp_gt_u32 s56, 41
	s_mov_b64 s[20:21], s[22:23]
	s_barrier
	s_cbranch_scc0 .LBB0_973
	s_setprio 0
	s_cmpk_gt_u32 s30, 0xff
	s_cbranch_scc1 .Lg973_nox
	s_barrier
	s_setprio 1
